# RWKV scan: capture-mask wrap by one s_lshr_b64 instead of two s_mov_b32 (on top of the dead barrier-add removal)
# speedup vs baseline: 1.0084x; 1.0010x over previous
.Lrw_fast:
	s_setprio 3
	s_and_b32 s89, s64, 1
	s_mul_i32 s89, s89, 0xc000
	v_lshl_add_u32 v112, s28, 5, v81
	v_lshl_add_u32 v124, v84, 2, s89
	v_lshl_add_u32 v135, v112, 2, s89
	ds_read_b128 v[76:79], v124 offset:272
	ds_read_b128 v[72:75], v124 offset:256
	ds_read_b128 v[68:71], v124 offset:512
	ds_read_b128 v[56:59], v124 offset:528
	ds_read2st64_b32 v[160:161], v135 offset0:5 offset1:11
	ds_read_b128 v[64:67], v124 offset:768
	ds_read_b128 v[60:63], v124 offset:784
	ds_read_b128 v[48:51], v124 offset:0
	ds_read_b128 v[40:43], v124 offset:16
	ds_read_b128 v[52:55], v124 offset:1040
	ds_read_b128 v[44:47], v124 offset:1024
	ds_read_b128 v[156:159], v124 offset:1808
	ds_read_b128 v[152:155], v124 offset:1792
	ds_read_b128 v[182:185], v124 offset:2048
	ds_read_b128 v[186:189], v124 offset:2064
	ds_read_b128 v[190:193], v124 offset:2304
	ds_read_b128 v[194:197], v124 offset:2320
	ds_read_b128 v[144:147], v124 offset:1536
	ds_read_b128 v[148:151], v124 offset:1552
	ds_read_b128 v[202:205], v124 offset:2576
	ds_read_b128 v[198:201], v124 offset:2560
	s_waitcnt lgkmcnt(10)
	v_pk_mul_f32 v[76:77], v[32:33], v[76:77]
	v_pk_mul_f32 v[78:79], v[34:35], v[78:79]
	v_pk_fma_f32 v[72:73], v[36:37], v[72:73], v[76:77]
	v_pk_fma_f32 v[74:75], v[38:39], v[74:75], v[78:79]
	v_pk_add_f32 v[72:73], v[72:73], v[74:75]
	v_add_f32_e32 v142, v72, v73
	s_nop 1
	v_add_f32_dpp v142, v142, v142 quad_perm:[1,0,3,2] row_mask:0xf bank_mask:0xf bound_ctrl:1
	s_nop 1
	v_add_f32_dpp v142, v142, v142 quad_perm:[2,3,0,1] row_mask:0xf bank_mask:0xf bound_ctrl:1
	s_nop 1
	v_add_f32_dpp v142, v142, v142 row_half_mirror row_mask:0xf bank_mask:0xf bound_ctrl:1
	v_pk_mul_f32 v[68:69], v[68:69], v[142:143] op_sel_hi:[1,0]
	v_pk_mul_f32 v[70:71], v[70:71], v[142:143] op_sel_hi:[1,0]
	v_pk_mul_f32 v[56:57], v[56:57], v[142:143] op_sel_hi:[1,0]
	v_pk_mul_f32 v[58:59], v[58:59], v[142:143] op_sel_hi:[1,0]
	v_pk_fma_f32 v[64:65], v[64:65], v[160:161], v[68:69] op_sel_hi:[1,0,1] neg_lo:[0,0,1] neg_hi:[0,0,1]
	v_pk_fma_f32 v[66:67], v[66:67], v[160:161], v[70:71] op_sel_hi:[1,0,1] neg_lo:[0,0,1] neg_hi:[0,0,1]
	v_pk_fma_f32 v[60:61], v[60:61], v[160:161], v[56:57] op_sel_hi:[1,0,1] neg_lo:[0,0,1] neg_hi:[0,0,1]
	v_pk_fma_f32 v[62:63], v[62:63], v[160:161], v[58:59] op_sel_hi:[1,0,1] neg_lo:[0,0,1] neg_hi:[0,0,1]
	v_pk_fma_f32 v[36:37], v[36:37], v[48:49], v[64:65]
	v_pk_fma_f32 v[38:39], v[38:39], v[50:51], v[66:67]
	v_pk_fma_f32 v[32:33], v[32:33], v[40:41], v[60:61]
	v_pk_fma_f32 v[34:35], v[34:35], v[42:43], v[62:63]
	s_waitcnt lgkmcnt(2)
	v_pk_mul_f32 v[156:157], v[32:33], v[156:157]
	v_pk_mul_f32 v[52:53], v[32:33], v[52:53]
	v_pk_mul_f32 v[158:159], v[34:35], v[158:159]
	v_pk_mul_f32 v[54:55], v[34:35], v[54:55]
	v_pk_fma_f32 v[152:153], v[36:37], v[152:153], v[156:157]
	v_pk_fma_f32 v[44:45], v[36:37], v[44:45], v[52:53]
	v_pk_fma_f32 v[154:155], v[38:39], v[154:155], v[158:159]
	v_pk_fma_f32 v[46:47], v[38:39], v[46:47], v[54:55]
	v_pk_add_f32 v[152:153], v[152:153], v[154:155]
	v_pk_add_f32 v[44:45], v[44:45], v[46:47]
	v_add_f32_e32 v142, v152, v153
	v_add_f32_e32 v143, v44, v45
	ds_read_b128 v[76:79], v124 offset:3344
	v_add_f32_dpp v142, v142, v142 quad_perm:[1,0,3,2] row_mask:0xf bank_mask:0xf bound_ctrl:1
	v_add_f32_dpp v143, v143, v143 quad_perm:[1,0,3,2] row_mask:0xf bank_mask:0xf bound_ctrl:1
	ds_read_b128 v[72:75], v124 offset:3328
	v_add_f32_dpp v142, v142, v142 quad_perm:[2,3,0,1] row_mask:0xf bank_mask:0xf bound_ctrl:1
	v_add_f32_dpp v143, v143, v143 quad_perm:[2,3,0,1] row_mask:0xf bank_mask:0xf bound_ctrl:1
	ds_read_b128 v[68:71], v124 offset:3584
	v_add_f32_dpp v142, v142, v142 row_half_mirror row_mask:0xf bank_mask:0xf bound_ctrl:1
	v_add_f32_dpp v143, v143, v143 row_half_mirror row_mask:0xf bank_mask:0xf bound_ctrl:1
	ds_read_b128 v[56:59], v124 offset:3600
	ds_read2st64_b32 v[126:127], v135 offset0:17 offset1:23
	ds_read_b128 v[64:67], v124 offset:3840
	ds_read_b128 v[60:63], v124 offset:3856
	ds_read_b128 v[48:51], v124 offset:3072
	ds_read_b128 v[40:43], v124 offset:3088
	v_pk_mul_f32 v[182:183], v[182:183], v[142:143] op_sel_hi:[1,0]
	v_pk_mul_f32 v[184:185], v[184:185], v[142:143] op_sel_hi:[1,0]
	s_mov_b32 vcc_lo, 0x1010101
	v_pk_mul_f32 v[186:187], v[186:187], v[142:143] op_sel_hi:[1,0]
	v_pk_mul_f32 v[188:189], v[188:189], v[142:143] op_sel_hi:[1,0]
	s_mov_b32 vcc_hi, 0x1010101
	v_pk_fma_f32 v[190:191], v[190:191], v[160:161], v[182:183] op_sel:[0,1,0] op_sel_hi:[1,1,1] neg_lo:[0,0,1] neg_hi:[0,0,1]
	v_pk_fma_f32 v[192:193], v[192:193], v[160:161], v[184:185] op_sel:[0,1,0] op_sel_hi:[1,1,1] neg_lo:[0,0,1] neg_hi:[0,0,1]
	v_cndmask_b32_e32 v134, v134, v143, vcc
	v_pk_fma_f32 v[194:195], v[194:195], v[160:161], v[186:187] op_sel:[0,1,0] op_sel_hi:[1,1,1] neg_lo:[0,0,1] neg_hi:[0,0,1]
	v_pk_fma_f32 v[196:197], v[196:197], v[160:161], v[188:189] op_sel:[0,1,0] op_sel_hi:[1,1,1] neg_lo:[0,0,1] neg_hi:[0,0,1]
	ds_read_b128 v[52:55], v124 offset:4112
	ds_read_b128 v[44:47], v124 offset:4096
	v_pk_fma_f32 v[36:37], v[36:37], v[144:145], v[190:191]
	v_pk_fma_f32 v[38:39], v[38:39], v[146:147], v[192:193]
	v_pk_fma_f32 v[32:33], v[32:33], v[148:149], v[194:195]
	v_pk_fma_f32 v[34:35], v[34:35], v[150:151], v[196:197]
	s_waitcnt lgkmcnt(2)
	v_pk_mul_f32 v[76:77], v[32:33], v[76:77]
	v_pk_mul_f32 v[202:203], v[32:33], v[202:203]
	v_pk_mul_f32 v[78:79], v[34:35], v[78:79]
	v_pk_mul_f32 v[204:205], v[34:35], v[204:205]
	v_pk_fma_f32 v[72:73], v[36:37], v[72:73], v[76:77]
	v_pk_fma_f32 v[198:199], v[36:37], v[198:199], v[202:203]
	v_pk_fma_f32 v[74:75], v[38:39], v[74:75], v[78:79]
	v_pk_fma_f32 v[200:201], v[38:39], v[200:201], v[204:205]
	v_pk_add_f32 v[72:73], v[72:73], v[74:75]
	v_pk_add_f32 v[198:199], v[198:199], v[200:201]
	v_add_f32_e32 v142, v72, v73
	v_add_f32_e32 v143, v198, v199
	ds_read_b128 v[156:159], v124 offset:4880
	v_add_f32_dpp v142, v142, v142 quad_perm:[1,0,3,2] row_mask:0xf bank_mask:0xf bound_ctrl:1
	v_add_f32_dpp v143, v143, v143 quad_perm:[1,0,3,2] row_mask:0xf bank_mask:0xf bound_ctrl:1
	ds_read_b128 v[152:155], v124 offset:4864
	v_add_f32_dpp v142, v142, v142 quad_perm:[2,3,0,1] row_mask:0xf bank_mask:0xf bound_ctrl:1
	v_add_f32_dpp v143, v143, v143 quad_perm:[2,3,0,1] row_mask:0xf bank_mask:0xf bound_ctrl:1
	ds_read_b128 v[182:185], v124 offset:5120
	v_add_f32_dpp v142, v142, v142 row_half_mirror row_mask:0xf bank_mask:0xf bound_ctrl:1
	v_add_f32_dpp v143, v143, v143 row_half_mirror row_mask:0xf bank_mask:0xf bound_ctrl:1
	ds_read_b128 v[186:189], v124 offset:5136
	ds_read_b128 v[190:193], v124 offset:5376
	ds_read_b128 v[194:197], v124 offset:5392
	ds_read_b128 v[144:147], v124 offset:4608
	ds_read_b128 v[148:151], v124 offset:4624
	v_pk_mul_f32 v[68:69], v[68:69], v[142:143] op_sel_hi:[1,0]
	v_pk_mul_f32 v[70:71], v[70:71], v[142:143] op_sel_hi:[1,0]
	s_lshl_b64 vcc, vcc, 1
	v_pk_mul_f32 v[56:57], v[56:57], v[142:143] op_sel_hi:[1,0]
	v_pk_mul_f32 v[58:59], v[58:59], v[142:143] op_sel_hi:[1,0]
	v_pk_fma_f32 v[64:65], v[64:65], v[126:127], v[68:69] op_sel_hi:[1,0,1] neg_lo:[0,0,1] neg_hi:[0,0,1]
	v_pk_fma_f32 v[66:67], v[66:67], v[126:127], v[70:71] op_sel_hi:[1,0,1] neg_lo:[0,0,1] neg_hi:[0,0,1]
	v_cndmask_b32_e32 v134, v134, v143, vcc
	v_pk_fma_f32 v[60:61], v[60:61], v[126:127], v[56:57] op_sel_hi:[1,0,1] neg_lo:[0,0,1] neg_hi:[0,0,1]
	v_pk_fma_f32 v[62:63], v[62:63], v[126:127], v[58:59] op_sel_hi:[1,0,1] neg_lo:[0,0,1] neg_hi:[0,0,1]
	ds_read_b128 v[202:205], v124 offset:5648
	ds_read_b128 v[198:201], v124 offset:5632
	v_pk_fma_f32 v[36:37], v[36:37], v[48:49], v[64:65]
	v_pk_fma_f32 v[38:39], v[38:39], v[50:51], v[66:67]
	v_pk_fma_f32 v[32:33], v[32:33], v[40:41], v[60:61]
	v_pk_fma_f32 v[34:35], v[34:35], v[42:43], v[62:63]
	s_waitcnt lgkmcnt(2)
	v_pk_mul_f32 v[156:157], v[32:33], v[156:157]
	v_pk_mul_f32 v[52:53], v[32:33], v[52:53]
	v_pk_mul_f32 v[158:159], v[34:35], v[158:159]
	v_pk_mul_f32 v[54:55], v[34:35], v[54:55]
	v_pk_fma_f32 v[152:153], v[36:37], v[152:153], v[156:157]
	v_pk_fma_f32 v[44:45], v[36:37], v[44:45], v[52:53]
	v_pk_fma_f32 v[154:155], v[38:39], v[154:155], v[158:159]
	v_pk_fma_f32 v[46:47], v[38:39], v[46:47], v[54:55]
	v_pk_add_f32 v[152:153], v[152:153], v[154:155]
	v_pk_add_f32 v[44:45], v[44:45], v[46:47]
	v_add_f32_e32 v142, v152, v153
	v_add_f32_e32 v143, v44, v45
	ds_read_b128 v[76:79], v124 offset:6416
	v_add_f32_dpp v142, v142, v142 quad_perm:[1,0,3,2] row_mask:0xf bank_mask:0xf bound_ctrl:1
	v_add_f32_dpp v143, v143, v143 quad_perm:[1,0,3,2] row_mask:0xf bank_mask:0xf bound_ctrl:1
	ds_read_b128 v[72:75], v124 offset:6400
	v_add_f32_dpp v142, v142, v142 quad_perm:[2,3,0,1] row_mask:0xf bank_mask:0xf bound_ctrl:1
	v_add_f32_dpp v143, v143, v143 quad_perm:[2,3,0,1] row_mask:0xf bank_mask:0xf bound_ctrl:1
	ds_read_b128 v[68:71], v124 offset:6656
	v_add_f32_dpp v142, v142, v142 row_half_mirror row_mask:0xf bank_mask:0xf bound_ctrl:1
	v_add_f32_dpp v143, v143, v143 row_half_mirror row_mask:0xf bank_mask:0xf bound_ctrl:1
	ds_read_b128 v[56:59], v124 offset:6672
	ds_read2st64_b32 v[160:161], v135 offset0:29 offset1:35
	ds_read_b128 v[64:67], v124 offset:6912
	ds_read_b128 v[60:63], v124 offset:6928
	ds_read_b128 v[48:51], v124 offset:6144
	ds_read_b128 v[40:43], v124 offset:6160
	v_pk_mul_f32 v[182:183], v[182:183], v[142:143] op_sel_hi:[1,0]
	v_pk_mul_f32 v[184:185], v[184:185], v[142:143] op_sel_hi:[1,0]
	s_lshl_b64 vcc, vcc, 1
	v_pk_mul_f32 v[186:187], v[186:187], v[142:143] op_sel_hi:[1,0]
	v_pk_mul_f32 v[188:189], v[188:189], v[142:143] op_sel_hi:[1,0]
	v_pk_fma_f32 v[190:191], v[190:191], v[126:127], v[182:183] op_sel:[0,1,0] op_sel_hi:[1,1,1] neg_lo:[0,0,1] neg_hi:[0,0,1]
	v_pk_fma_f32 v[192:193], v[192:193], v[126:127], v[184:185] op_sel:[0,1,0] op_sel_hi:[1,1,1] neg_lo:[0,0,1] neg_hi:[0,0,1]
	v_cndmask_b32_e32 v134, v134, v143, vcc
	v_pk_fma_f32 v[194:195], v[194:195], v[126:127], v[186:187] op_sel:[0,1,0] op_sel_hi:[1,1,1] neg_lo:[0,0,1] neg_hi:[0,0,1]
	v_pk_fma_f32 v[196:197], v[196:197], v[126:127], v[188:189] op_sel:[0,1,0] op_sel_hi:[1,1,1] neg_lo:[0,0,1] neg_hi:[0,0,1]
	ds_read_b128 v[52:55], v124 offset:7184
	ds_read_b128 v[44:47], v124 offset:7168
	v_pk_fma_f32 v[36:37], v[36:37], v[144:145], v[190:191]
	v_pk_fma_f32 v[38:39], v[38:39], v[146:147], v[192:193]
	v_pk_fma_f32 v[32:33], v[32:33], v[148:149], v[194:195]
	v_pk_fma_f32 v[34:35], v[34:35], v[150:151], v[196:197]
	s_waitcnt lgkmcnt(2)
	v_pk_mul_f32 v[76:77], v[32:33], v[76:77]
	v_pk_mul_f32 v[202:203], v[32:33], v[202:203]
	v_pk_mul_f32 v[78:79], v[34:35], v[78:79]
	v_pk_mul_f32 v[204:205], v[34:35], v[204:205]
	v_pk_fma_f32 v[72:73], v[36:37], v[72:73], v[76:77]
	v_pk_fma_f32 v[198:199], v[36:37], v[198:199], v[202:203]
	v_pk_fma_f32 v[74:75], v[38:39], v[74:75], v[78:79]
	v_pk_fma_f32 v[200:201], v[38:39], v[200:201], v[204:205]
	v_pk_add_f32 v[72:73], v[72:73], v[74:75]
	v_pk_add_f32 v[198:199], v[198:199], v[200:201]
	v_add_f32_e32 v142, v72, v73
	v_add_f32_e32 v143, v198, v199
	ds_read_b128 v[156:159], v124 offset:7952
	v_add_f32_dpp v142, v142, v142 quad_perm:[1,0,3,2] row_mask:0xf bank_mask:0xf bound_ctrl:1
	v_add_f32_dpp v143, v143, v143 quad_perm:[1,0,3,2] row_mask:0xf bank_mask:0xf bound_ctrl:1
	ds_read_b128 v[152:155], v124 offset:7936
	v_add_f32_dpp v142, v142, v142 quad_perm:[2,3,0,1] row_mask:0xf bank_mask:0xf bound_ctrl:1
	v_add_f32_dpp v143, v143, v143 quad_perm:[2,3,0,1] row_mask:0xf bank_mask:0xf bound_ctrl:1
	ds_read_b128 v[182:185], v124 offset:8192
	v_add_f32_dpp v142, v142, v142 row_half_mirror row_mask:0xf bank_mask:0xf bound_ctrl:1
	v_add_f32_dpp v143, v143, v143 row_half_mirror row_mask:0xf bank_mask:0xf bound_ctrl:1
	ds_read_b128 v[186:189], v124 offset:8208
	ds_read_b128 v[190:193], v124 offset:8448
	ds_read_b128 v[194:197], v124 offset:8464
	ds_read_b128 v[144:147], v124 offset:7680
	ds_read_b128 v[148:151], v124 offset:7696
	v_pk_mul_f32 v[68:69], v[68:69], v[142:143] op_sel_hi:[1,0]
	v_pk_mul_f32 v[70:71], v[70:71], v[142:143] op_sel_hi:[1,0]
	s_lshl_b64 vcc, vcc, 1
	v_pk_mul_f32 v[56:57], v[56:57], v[142:143] op_sel_hi:[1,0]
	v_pk_mul_f32 v[58:59], v[58:59], v[142:143] op_sel_hi:[1,0]
	v_pk_fma_f32 v[64:65], v[64:65], v[160:161], v[68:69] op_sel_hi:[1,0,1] neg_lo:[0,0,1] neg_hi:[0,0,1]
	v_pk_fma_f32 v[66:67], v[66:67], v[160:161], v[70:71] op_sel_hi:[1,0,1] neg_lo:[0,0,1] neg_hi:[0,0,1]
	v_cndmask_b32_e32 v134, v134, v143, vcc
	v_pk_fma_f32 v[60:61], v[60:61], v[160:161], v[56:57] op_sel_hi:[1,0,1] neg_lo:[0,0,1] neg_hi:[0,0,1]
	v_pk_fma_f32 v[62:63], v[62:63], v[160:161], v[58:59] op_sel_hi:[1,0,1] neg_lo:[0,0,1] neg_hi:[0,0,1]
	ds_read_b128 v[202:205], v124 offset:8720
	ds_read_b128 v[198:201], v124 offset:8704
	v_pk_fma_f32 v[36:37], v[36:37], v[48:49], v[64:65]
	v_pk_fma_f32 v[38:39], v[38:39], v[50:51], v[66:67]
	v_pk_fma_f32 v[32:33], v[32:33], v[40:41], v[60:61]
	v_pk_fma_f32 v[34:35], v[34:35], v[42:43], v[62:63]
	s_waitcnt lgkmcnt(2)
	v_pk_mul_f32 v[156:157], v[32:33], v[156:157]
	v_pk_mul_f32 v[52:53], v[32:33], v[52:53]
	v_pk_mul_f32 v[158:159], v[34:35], v[158:159]
	v_pk_mul_f32 v[54:55], v[34:35], v[54:55]
	v_pk_fma_f32 v[152:153], v[36:37], v[152:153], v[156:157]
	v_pk_fma_f32 v[44:45], v[36:37], v[44:45], v[52:53]
	v_pk_fma_f32 v[154:155], v[38:39], v[154:155], v[158:159]
	v_pk_fma_f32 v[46:47], v[38:39], v[46:47], v[54:55]
	v_pk_add_f32 v[152:153], v[152:153], v[154:155]
	v_pk_add_f32 v[44:45], v[44:45], v[46:47]
	v_add_f32_e32 v142, v152, v153
	v_add_f32_e32 v143, v44, v45
	ds_read_b128 v[76:79], v124 offset:9488
	v_add_f32_dpp v142, v142, v142 quad_perm:[1,0,3,2] row_mask:0xf bank_mask:0xf bound_ctrl:1
	v_add_f32_dpp v143, v143, v143 quad_perm:[1,0,3,2] row_mask:0xf bank_mask:0xf bound_ctrl:1
	ds_read_b128 v[72:75], v124 offset:9472
	v_add_f32_dpp v142, v142, v142 quad_perm:[2,3,0,1] row_mask:0xf bank_mask:0xf bound_ctrl:1
	v_add_f32_dpp v143, v143, v143 quad_perm:[2,3,0,1] row_mask:0xf bank_mask:0xf bound_ctrl:1
	ds_read_b128 v[68:71], v124 offset:9728
	v_add_f32_dpp v142, v142, v142 row_half_mirror row_mask:0xf bank_mask:0xf bound_ctrl:1
	v_add_f32_dpp v143, v143, v143 row_half_mirror row_mask:0xf bank_mask:0xf bound_ctrl:1
	ds_read_b128 v[56:59], v124 offset:9744
	ds_read2st64_b32 v[126:127], v135 offset0:41 offset1:47
	ds_read_b128 v[64:67], v124 offset:9984
	ds_read_b128 v[60:63], v124 offset:10000
	ds_read_b128 v[48:51], v124 offset:9216
	ds_read_b128 v[40:43], v124 offset:9232
	v_pk_mul_f32 v[182:183], v[182:183], v[142:143] op_sel_hi:[1,0]
	v_pk_mul_f32 v[184:185], v[184:185], v[142:143] op_sel_hi:[1,0]
	s_lshl_b64 vcc, vcc, 1
	v_pk_mul_f32 v[186:187], v[186:187], v[142:143] op_sel_hi:[1,0]
	v_pk_mul_f32 v[188:189], v[188:189], v[142:143] op_sel_hi:[1,0]
	v_pk_fma_f32 v[190:191], v[190:191], v[160:161], v[182:183] op_sel:[0,1,0] op_sel_hi:[1,1,1] neg_lo:[0,0,1] neg_hi:[0,0,1]
	v_pk_fma_f32 v[192:193], v[192:193], v[160:161], v[184:185] op_sel:[0,1,0] op_sel_hi:[1,1,1] neg_lo:[0,0,1] neg_hi:[0,0,1]
	v_cndmask_b32_e32 v134, v134, v143, vcc
	v_pk_fma_f32 v[194:195], v[194:195], v[160:161], v[186:187] op_sel:[0,1,0] op_sel_hi:[1,1,1] neg_lo:[0,0,1] neg_hi:[0,0,1]
	v_pk_fma_f32 v[196:197], v[196:197], v[160:161], v[188:189] op_sel:[0,1,0] op_sel_hi:[1,1,1] neg_lo:[0,0,1] neg_hi:[0,0,1]
	ds_read_b128 v[52:55], v124 offset:10256
	ds_read_b128 v[44:47], v124 offset:10240
	v_pk_fma_f32 v[36:37], v[36:37], v[144:145], v[190:191]
	v_pk_fma_f32 v[38:39], v[38:39], v[146:147], v[192:193]
	v_pk_fma_f32 v[32:33], v[32:33], v[148:149], v[194:195]
	v_pk_fma_f32 v[34:35], v[34:35], v[150:151], v[196:197]
	s_waitcnt lgkmcnt(2)
	v_pk_mul_f32 v[76:77], v[32:33], v[76:77]
	v_pk_mul_f32 v[202:203], v[32:33], v[202:203]
	v_pk_mul_f32 v[78:79], v[34:35], v[78:79]
	v_pk_mul_f32 v[204:205], v[34:35], v[204:205]
	v_pk_fma_f32 v[72:73], v[36:37], v[72:73], v[76:77]
	v_pk_fma_f32 v[198:199], v[36:37], v[198:199], v[202:203]
	v_pk_fma_f32 v[74:75], v[38:39], v[74:75], v[78:79]
	v_pk_fma_f32 v[200:201], v[38:39], v[200:201], v[204:205]
	v_pk_add_f32 v[72:73], v[72:73], v[74:75]
	v_pk_add_f32 v[198:199], v[198:199], v[200:201]
	v_add_f32_e32 v142, v72, v73
	v_add_f32_e32 v143, v198, v199
	ds_read_b128 v[156:159], v124 offset:11024
	v_add_f32_dpp v142, v142, v142 quad_perm:[1,0,3,2] row_mask:0xf bank_mask:0xf bound_ctrl:1
	v_add_f32_dpp v143, v143, v143 quad_perm:[1,0,3,2] row_mask:0xf bank_mask:0xf bound_ctrl:1
	ds_read_b128 v[152:155], v124 offset:11008
	v_add_f32_dpp v142, v142, v142 quad_perm:[2,3,0,1] row_mask:0xf bank_mask:0xf bound_ctrl:1
	v_add_f32_dpp v143, v143, v143 quad_perm:[2,3,0,1] row_mask:0xf bank_mask:0xf bound_ctrl:1
	ds_read_b128 v[182:185], v124 offset:11264
	v_add_f32_dpp v142, v142, v142 row_half_mirror row_mask:0xf bank_mask:0xf bound_ctrl:1
	v_add_f32_dpp v143, v143, v143 row_half_mirror row_mask:0xf bank_mask:0xf bound_ctrl:1
	ds_read_b128 v[186:189], v124 offset:11280
	ds_read_b128 v[190:193], v124 offset:11520
	ds_read_b128 v[194:197], v124 offset:11536
	ds_read_b128 v[144:147], v124 offset:10752
	ds_read_b128 v[148:151], v124 offset:10768
	v_pk_mul_f32 v[68:69], v[68:69], v[142:143] op_sel_hi:[1,0]
	v_pk_mul_f32 v[70:71], v[70:71], v[142:143] op_sel_hi:[1,0]
	s_lshl_b64 vcc, vcc, 1
	v_pk_mul_f32 v[56:57], v[56:57], v[142:143] op_sel_hi:[1,0]
	v_pk_mul_f32 v[58:59], v[58:59], v[142:143] op_sel_hi:[1,0]
	v_pk_fma_f32 v[64:65], v[64:65], v[126:127], v[68:69] op_sel_hi:[1,0,1] neg_lo:[0,0,1] neg_hi:[0,0,1]
	v_pk_fma_f32 v[66:67], v[66:67], v[126:127], v[70:71] op_sel_hi:[1,0,1] neg_lo:[0,0,1] neg_hi:[0,0,1]
	v_cndmask_b32_e32 v134, v134, v143, vcc
	v_pk_fma_f32 v[60:61], v[60:61], v[126:127], v[56:57] op_sel_hi:[1,0,1] neg_lo:[0,0,1] neg_hi:[0,0,1]
	v_pk_fma_f32 v[62:63], v[62:63], v[126:127], v[58:59] op_sel_hi:[1,0,1] neg_lo:[0,0,1] neg_hi:[0,0,1]
	ds_read_b128 v[202:205], v124 offset:11792
	ds_read_b128 v[198:201], v124 offset:11776
	v_pk_fma_f32 v[36:37], v[36:37], v[48:49], v[64:65]
	v_pk_fma_f32 v[38:39], v[38:39], v[50:51], v[66:67]
	v_pk_fma_f32 v[32:33], v[32:33], v[40:41], v[60:61]
	v_pk_fma_f32 v[34:35], v[34:35], v[42:43], v[62:63]
	s_waitcnt lgkmcnt(2)
	v_pk_mul_f32 v[156:157], v[32:33], v[156:157]
	v_pk_mul_f32 v[52:53], v[32:33], v[52:53]
	v_pk_mul_f32 v[158:159], v[34:35], v[158:159]
	v_pk_mul_f32 v[54:55], v[34:35], v[54:55]
	v_pk_fma_f32 v[152:153], v[36:37], v[152:153], v[156:157]
	v_pk_fma_f32 v[44:45], v[36:37], v[44:45], v[52:53]
	v_pk_fma_f32 v[154:155], v[38:39], v[154:155], v[158:159]
	v_pk_fma_f32 v[46:47], v[38:39], v[46:47], v[54:55]
	v_pk_add_f32 v[152:153], v[152:153], v[154:155]
	v_pk_add_f32 v[44:45], v[44:45], v[46:47]
	v_add_f32_e32 v142, v152, v153
	v_add_f32_e32 v143, v44, v45
	ds_read_b128 v[76:79], v124 offset:12560
	v_add_f32_dpp v142, v142, v142 quad_perm:[1,0,3,2] row_mask:0xf bank_mask:0xf bound_ctrl:1
	v_add_f32_dpp v143, v143, v143 quad_perm:[1,0,3,2] row_mask:0xf bank_mask:0xf bound_ctrl:1
	ds_read_b128 v[72:75], v124 offset:12544
	v_add_f32_dpp v142, v142, v142 quad_perm:[2,3,0,1] row_mask:0xf bank_mask:0xf bound_ctrl:1
	v_add_f32_dpp v143, v143, v143 quad_perm:[2,3,0,1] row_mask:0xf bank_mask:0xf bound_ctrl:1
	ds_read_b128 v[68:71], v124 offset:12800
	v_add_f32_dpp v142, v142, v142 row_half_mirror row_mask:0xf bank_mask:0xf bound_ctrl:1
	v_add_f32_dpp v143, v143, v143 row_half_mirror row_mask:0xf bank_mask:0xf bound_ctrl:1
	ds_read_b128 v[56:59], v124 offset:12816
	ds_read2st64_b32 v[160:161], v135 offset0:53 offset1:59
	ds_read_b128 v[64:67], v124 offset:13056
	ds_read_b128 v[60:63], v124 offset:13072
	ds_read_b128 v[48:51], v124 offset:12288
	ds_read_b128 v[40:43], v124 offset:12304
	v_pk_mul_f32 v[182:183], v[182:183], v[142:143] op_sel_hi:[1,0]
	v_pk_mul_f32 v[184:185], v[184:185], v[142:143] op_sel_hi:[1,0]
	s_lshl_b64 vcc, vcc, 1
	v_pk_mul_f32 v[186:187], v[186:187], v[142:143] op_sel_hi:[1,0]
	v_pk_mul_f32 v[188:189], v[188:189], v[142:143] op_sel_hi:[1,0]
	v_pk_fma_f32 v[190:191], v[190:191], v[126:127], v[182:183] op_sel:[0,1,0] op_sel_hi:[1,1,1] neg_lo:[0,0,1] neg_hi:[0,0,1]
	v_pk_fma_f32 v[192:193], v[192:193], v[126:127], v[184:185] op_sel:[0,1,0] op_sel_hi:[1,1,1] neg_lo:[0,0,1] neg_hi:[0,0,1]
	v_cndmask_b32_e32 v134, v134, v143, vcc
	v_pk_fma_f32 v[194:195], v[194:195], v[126:127], v[186:187] op_sel:[0,1,0] op_sel_hi:[1,1,1] neg_lo:[0,0,1] neg_hi:[0,0,1]
	v_pk_fma_f32 v[196:197], v[196:197], v[126:127], v[188:189] op_sel:[0,1,0] op_sel_hi:[1,1,1] neg_lo:[0,0,1] neg_hi:[0,0,1]
	ds_read_b128 v[52:55], v124 offset:13328
	ds_read_b128 v[44:47], v124 offset:13312
	v_pk_fma_f32 v[36:37], v[36:37], v[144:145], v[190:191]
	v_pk_fma_f32 v[38:39], v[38:39], v[146:147], v[192:193]
	v_pk_fma_f32 v[32:33], v[32:33], v[148:149], v[194:195]
	v_pk_fma_f32 v[34:35], v[34:35], v[150:151], v[196:197]
	s_waitcnt lgkmcnt(2)
	v_pk_mul_f32 v[76:77], v[32:33], v[76:77]
	v_pk_mul_f32 v[202:203], v[32:33], v[202:203]
	v_pk_mul_f32 v[78:79], v[34:35], v[78:79]
	v_pk_mul_f32 v[204:205], v[34:35], v[204:205]
	v_pk_fma_f32 v[72:73], v[36:37], v[72:73], v[76:77]
	v_pk_fma_f32 v[198:199], v[36:37], v[198:199], v[202:203]
	v_pk_fma_f32 v[74:75], v[38:39], v[74:75], v[78:79]
	v_pk_fma_f32 v[200:201], v[38:39], v[200:201], v[204:205]
	v_pk_add_f32 v[72:73], v[72:73], v[74:75]
	v_pk_add_f32 v[198:199], v[198:199], v[200:201]
	v_add_f32_e32 v142, v72, v73
	v_add_f32_e32 v143, v198, v199
	ds_read_b128 v[156:159], v124 offset:14096
	v_add_f32_dpp v142, v142, v142 quad_perm:[1,0,3,2] row_mask:0xf bank_mask:0xf bound_ctrl:1
	v_add_f32_dpp v143, v143, v143 quad_perm:[1,0,3,2] row_mask:0xf bank_mask:0xf bound_ctrl:1
	ds_read_b128 v[152:155], v124 offset:14080
	v_add_f32_dpp v142, v142, v142 quad_perm:[2,3,0,1] row_mask:0xf bank_mask:0xf bound_ctrl:1
	v_add_f32_dpp v143, v143, v143 quad_perm:[2,3,0,1] row_mask:0xf bank_mask:0xf bound_ctrl:1
	ds_read_b128 v[182:185], v124 offset:14336
	v_add_f32_dpp v142, v142, v142 row_half_mirror row_mask:0xf bank_mask:0xf bound_ctrl:1
	v_add_f32_dpp v143, v143, v143 row_half_mirror row_mask:0xf bank_mask:0xf bound_ctrl:1
	ds_read_b128 v[186:189], v124 offset:14352
	ds_read_b128 v[190:193], v124 offset:14592
	ds_read_b128 v[194:197], v124 offset:14608
	ds_read_b128 v[144:147], v124 offset:13824
	ds_read_b128 v[148:151], v124 offset:13840
	v_pk_mul_f32 v[68:69], v[68:69], v[142:143] op_sel_hi:[1,0]
	v_pk_mul_f32 v[70:71], v[70:71], v[142:143] op_sel_hi:[1,0]
	s_lshl_b64 vcc, vcc, 1
	v_pk_mul_f32 v[56:57], v[56:57], v[142:143] op_sel_hi:[1,0]
	v_pk_mul_f32 v[58:59], v[58:59], v[142:143] op_sel_hi:[1,0]
	v_pk_fma_f32 v[64:65], v[64:65], v[160:161], v[68:69] op_sel_hi:[1,0,1] neg_lo:[0,0,1] neg_hi:[0,0,1]
	v_pk_fma_f32 v[66:67], v[66:67], v[160:161], v[70:71] op_sel_hi:[1,0,1] neg_lo:[0,0,1] neg_hi:[0,0,1]
	v_cndmask_b32_e32 v134, v134, v143, vcc
	v_pk_fma_f32 v[60:61], v[60:61], v[160:161], v[56:57] op_sel_hi:[1,0,1] neg_lo:[0,0,1] neg_hi:[0,0,1]
	v_pk_fma_f32 v[62:63], v[62:63], v[160:161], v[58:59] op_sel_hi:[1,0,1] neg_lo:[0,0,1] neg_hi:[0,0,1]
	ds_read_b128 v[202:205], v124 offset:14864
	ds_read_b128 v[198:201], v124 offset:14848
	v_pk_fma_f32 v[36:37], v[36:37], v[48:49], v[64:65]
	v_pk_fma_f32 v[38:39], v[38:39], v[50:51], v[66:67]
	v_pk_fma_f32 v[32:33], v[32:33], v[40:41], v[60:61]
	v_pk_fma_f32 v[34:35], v[34:35], v[42:43], v[62:63]
	s_waitcnt lgkmcnt(2)
	v_pk_mul_f32 v[156:157], v[32:33], v[156:157]
	v_pk_mul_f32 v[52:53], v[32:33], v[52:53]
	v_pk_mul_f32 v[158:159], v[34:35], v[158:159]
	v_pk_mul_f32 v[54:55], v[34:35], v[54:55]
	v_pk_fma_f32 v[152:153], v[36:37], v[152:153], v[156:157]
	v_pk_fma_f32 v[44:45], v[36:37], v[44:45], v[52:53]
	v_pk_fma_f32 v[154:155], v[38:39], v[154:155], v[158:159]
	v_pk_fma_f32 v[46:47], v[38:39], v[46:47], v[54:55]
	v_pk_add_f32 v[152:153], v[152:153], v[154:155]
	v_pk_add_f32 v[44:45], v[44:45], v[46:47]
	v_add_f32_e32 v142, v152, v153
	v_add_f32_e32 v143, v44, v45
	ds_read_b128 v[76:79], v124 offset:15632
	v_add_f32_dpp v142, v142, v142 quad_perm:[1,0,3,2] row_mask:0xf bank_mask:0xf bound_ctrl:1
	v_add_f32_dpp v143, v143, v143 quad_perm:[1,0,3,2] row_mask:0xf bank_mask:0xf bound_ctrl:1
	ds_read_b128 v[72:75], v124 offset:15616
	v_add_f32_dpp v142, v142, v142 quad_perm:[2,3,0,1] row_mask:0xf bank_mask:0xf bound_ctrl:1
	v_add_f32_dpp v143, v143, v143 quad_perm:[2,3,0,1] row_mask:0xf bank_mask:0xf bound_ctrl:1
	ds_read_b128 v[68:71], v124 offset:15872
	v_add_f32_dpp v142, v142, v142 row_half_mirror row_mask:0xf bank_mask:0xf bound_ctrl:1
	v_add_f32_dpp v143, v143, v143 row_half_mirror row_mask:0xf bank_mask:0xf bound_ctrl:1
	ds_read_b128 v[56:59], v124 offset:15888
	ds_read2st64_b32 v[126:127], v135 offset0:65 offset1:71
	ds_read_b128 v[64:67], v124 offset:16128
	ds_read_b128 v[60:63], v124 offset:16144
	ds_read_b128 v[48:51], v124 offset:15360
	ds_read_b128 v[40:43], v124 offset:15376
	v_pk_mul_f32 v[182:183], v[182:183], v[142:143] op_sel_hi:[1,0]
	v_pk_mul_f32 v[184:185], v[184:185], v[142:143] op_sel_hi:[1,0]
	s_lshr_b64 vcc, vcc, 7
	v_pk_mul_f32 v[186:187], v[186:187], v[142:143] op_sel_hi:[1,0]
	v_pk_mul_f32 v[188:189], v[188:189], v[142:143] op_sel_hi:[1,0]
	v_pk_fma_f32 v[190:191], v[190:191], v[160:161], v[182:183] op_sel:[0,1,0] op_sel_hi:[1,1,1] neg_lo:[0,0,1] neg_hi:[0,0,1]
	v_pk_fma_f32 v[192:193], v[192:193], v[160:161], v[184:185] op_sel:[0,1,0] op_sel_hi:[1,1,1] neg_lo:[0,0,1] neg_hi:[0,0,1]
	v_cndmask_b32_e32 v133, v133, v143, vcc
	v_pk_fma_f32 v[194:195], v[194:195], v[160:161], v[186:187] op_sel:[0,1,0] op_sel_hi:[1,1,1] neg_lo:[0,0,1] neg_hi:[0,0,1]
	v_pk_fma_f32 v[196:197], v[196:197], v[160:161], v[188:189] op_sel:[0,1,0] op_sel_hi:[1,1,1] neg_lo:[0,0,1] neg_hi:[0,0,1]
	ds_read_b128 v[52:55], v124 offset:16400
	ds_read_b128 v[44:47], v124 offset:16384
	v_pk_fma_f32 v[36:37], v[36:37], v[144:145], v[190:191]
	v_pk_fma_f32 v[38:39], v[38:39], v[146:147], v[192:193]
	v_pk_fma_f32 v[32:33], v[32:33], v[148:149], v[194:195]
	v_pk_fma_f32 v[34:35], v[34:35], v[150:151], v[196:197]
	s_waitcnt lgkmcnt(2)
	v_pk_mul_f32 v[76:77], v[32:33], v[76:77]
	v_pk_mul_f32 v[202:203], v[32:33], v[202:203]
	v_pk_mul_f32 v[78:79], v[34:35], v[78:79]
	v_pk_mul_f32 v[204:205], v[34:35], v[204:205]
	v_pk_fma_f32 v[72:73], v[36:37], v[72:73], v[76:77]
	v_pk_fma_f32 v[198:199], v[36:37], v[198:199], v[202:203]
	v_pk_fma_f32 v[74:75], v[38:39], v[74:75], v[78:79]
	v_pk_fma_f32 v[200:201], v[38:39], v[200:201], v[204:205]
	v_pk_add_f32 v[72:73], v[72:73], v[74:75]
	v_pk_add_f32 v[198:199], v[198:199], v[200:201]
	v_add_f32_e32 v142, v72, v73
	v_add_f32_e32 v143, v198, v199
	ds_read_b128 v[156:159], v124 offset:17168
	v_add_f32_dpp v142, v142, v142 quad_perm:[1,0,3,2] row_mask:0xf bank_mask:0xf bound_ctrl:1
	v_add_f32_dpp v143, v143, v143 quad_perm:[1,0,3,2] row_mask:0xf bank_mask:0xf bound_ctrl:1
	ds_read_b128 v[152:155], v124 offset:17152
	v_add_f32_dpp v142, v142, v142 quad_perm:[2,3,0,1] row_mask:0xf bank_mask:0xf bound_ctrl:1
	v_add_f32_dpp v143, v143, v143 quad_perm:[2,3,0,1] row_mask:0xf bank_mask:0xf bound_ctrl:1
	ds_read_b128 v[182:185], v124 offset:17408
	v_add_f32_dpp v142, v142, v142 row_half_mirror row_mask:0xf bank_mask:0xf bound_ctrl:1
	v_add_f32_dpp v143, v143, v143 row_half_mirror row_mask:0xf bank_mask:0xf bound_ctrl:1
	ds_read_b128 v[186:189], v124 offset:17424
	ds_read_b128 v[190:193], v124 offset:17664
	ds_read_b128 v[194:197], v124 offset:17680
	ds_read_b128 v[144:147], v124 offset:16896
	ds_read_b128 v[148:151], v124 offset:16912
	v_pk_mul_f32 v[68:69], v[68:69], v[142:143] op_sel_hi:[1,0]
	v_pk_mul_f32 v[70:71], v[70:71], v[142:143] op_sel_hi:[1,0]
	s_lshl_b64 vcc, vcc, 1
	v_pk_mul_f32 v[56:57], v[56:57], v[142:143] op_sel_hi:[1,0]
	v_pk_mul_f32 v[58:59], v[58:59], v[142:143] op_sel_hi:[1,0]
	v_pk_fma_f32 v[64:65], v[64:65], v[126:127], v[68:69] op_sel_hi:[1,0,1] neg_lo:[0,0,1] neg_hi:[0,0,1]
	v_pk_fma_f32 v[66:67], v[66:67], v[126:127], v[70:71] op_sel_hi:[1,0,1] neg_lo:[0,0,1] neg_hi:[0,0,1]
	v_cndmask_b32_e32 v133, v133, v143, vcc
	v_pk_fma_f32 v[60:61], v[60:61], v[126:127], v[56:57] op_sel_hi:[1,0,1] neg_lo:[0,0,1] neg_hi:[0,0,1]
	v_pk_fma_f32 v[62:63], v[62:63], v[126:127], v[58:59] op_sel_hi:[1,0,1] neg_lo:[0,0,1] neg_hi:[0,0,1]
	ds_read_b128 v[202:205], v124 offset:17936
	ds_read_b128 v[198:201], v124 offset:17920
	v_pk_fma_f32 v[36:37], v[36:37], v[48:49], v[64:65]
	v_pk_fma_f32 v[38:39], v[38:39], v[50:51], v[66:67]
	v_pk_fma_f32 v[32:33], v[32:33], v[40:41], v[60:61]
	v_pk_fma_f32 v[34:35], v[34:35], v[42:43], v[62:63]
	s_waitcnt lgkmcnt(2)
	v_pk_mul_f32 v[156:157], v[32:33], v[156:157]
	v_pk_mul_f32 v[52:53], v[32:33], v[52:53]
	v_pk_mul_f32 v[158:159], v[34:35], v[158:159]
	v_pk_mul_f32 v[54:55], v[34:35], v[54:55]
	v_pk_fma_f32 v[152:153], v[36:37], v[152:153], v[156:157]
	v_pk_fma_f32 v[44:45], v[36:37], v[44:45], v[52:53]
	v_pk_fma_f32 v[154:155], v[38:39], v[154:155], v[158:159]
	v_pk_fma_f32 v[46:47], v[38:39], v[46:47], v[54:55]
	v_pk_add_f32 v[152:153], v[152:153], v[154:155]
	v_pk_add_f32 v[44:45], v[44:45], v[46:47]
	v_add_f32_e32 v142, v152, v153
	v_add_f32_e32 v143, v44, v45
	ds_read_b128 v[76:79], v124 offset:18704
	v_add_f32_dpp v142, v142, v142 quad_perm:[1,0,3,2] row_mask:0xf bank_mask:0xf bound_ctrl:1
	v_add_f32_dpp v143, v143, v143 quad_perm:[1,0,3,2] row_mask:0xf bank_mask:0xf bound_ctrl:1
	ds_read_b128 v[72:75], v124 offset:18688
	v_add_f32_dpp v142, v142, v142 quad_perm:[2,3,0,1] row_mask:0xf bank_mask:0xf bound_ctrl:1
	v_add_f32_dpp v143, v143, v143 quad_perm:[2,3,0,1] row_mask:0xf bank_mask:0xf bound_ctrl:1
	ds_read_b128 v[68:71], v124 offset:18944
	v_add_f32_dpp v142, v142, v142 row_half_mirror row_mask:0xf bank_mask:0xf bound_ctrl:1
	v_add_f32_dpp v143, v143, v143 row_half_mirror row_mask:0xf bank_mask:0xf bound_ctrl:1
	ds_read_b128 v[56:59], v124 offset:18960
	ds_read2st64_b32 v[160:161], v135 offset0:77 offset1:83
	ds_read_b128 v[64:67], v124 offset:19200
	ds_read_b128 v[60:63], v124 offset:19216
	ds_read_b128 v[48:51], v124 offset:18432
	ds_read_b128 v[40:43], v124 offset:18448
	v_pk_mul_f32 v[182:183], v[182:183], v[142:143] op_sel_hi:[1,0]
	v_pk_mul_f32 v[184:185], v[184:185], v[142:143] op_sel_hi:[1,0]
	s_lshl_b64 vcc, vcc, 1
	v_pk_mul_f32 v[186:187], v[186:187], v[142:143] op_sel_hi:[1,0]
	v_pk_mul_f32 v[188:189], v[188:189], v[142:143] op_sel_hi:[1,0]
	v_pk_fma_f32 v[190:191], v[190:191], v[126:127], v[182:183] op_sel:[0,1,0] op_sel_hi:[1,1,1] neg_lo:[0,0,1] neg_hi:[0,0,1]
	v_pk_fma_f32 v[192:193], v[192:193], v[126:127], v[184:185] op_sel:[0,1,0] op_sel_hi:[1,1,1] neg_lo:[0,0,1] neg_hi:[0,0,1]
	v_cndmask_b32_e32 v133, v133, v143, vcc
	v_pk_fma_f32 v[194:195], v[194:195], v[126:127], v[186:187] op_sel:[0,1,0] op_sel_hi:[1,1,1] neg_lo:[0,0,1] neg_hi:[0,0,1]
	v_pk_fma_f32 v[196:197], v[196:197], v[126:127], v[188:189] op_sel:[0,1,0] op_sel_hi:[1,1,1] neg_lo:[0,0,1] neg_hi:[0,0,1]
	ds_read_b128 v[52:55], v124 offset:19472
	ds_read_b128 v[44:47], v124 offset:19456
	v_pk_fma_f32 v[36:37], v[36:37], v[144:145], v[190:191]
	v_pk_fma_f32 v[38:39], v[38:39], v[146:147], v[192:193]
	v_pk_fma_f32 v[32:33], v[32:33], v[148:149], v[194:195]
	v_pk_fma_f32 v[34:35], v[34:35], v[150:151], v[196:197]
	s_waitcnt lgkmcnt(2)
	v_pk_mul_f32 v[76:77], v[32:33], v[76:77]
	v_pk_mul_f32 v[202:203], v[32:33], v[202:203]
	v_pk_mul_f32 v[78:79], v[34:35], v[78:79]
	v_pk_mul_f32 v[204:205], v[34:35], v[204:205]
	v_pk_fma_f32 v[72:73], v[36:37], v[72:73], v[76:77]
	v_pk_fma_f32 v[198:199], v[36:37], v[198:199], v[202:203]
	v_pk_fma_f32 v[74:75], v[38:39], v[74:75], v[78:79]
	v_pk_fma_f32 v[200:201], v[38:39], v[200:201], v[204:205]
	v_pk_add_f32 v[72:73], v[72:73], v[74:75]
	v_pk_add_f32 v[198:199], v[198:199], v[200:201]
	v_add_f32_e32 v142, v72, v73
	v_add_f32_e32 v143, v198, v199
	ds_read_b128 v[156:159], v124 offset:20240
	v_add_f32_dpp v142, v142, v142 quad_perm:[1,0,3,2] row_mask:0xf bank_mask:0xf bound_ctrl:1
	v_add_f32_dpp v143, v143, v143 quad_perm:[1,0,3,2] row_mask:0xf bank_mask:0xf bound_ctrl:1
	ds_read_b128 v[152:155], v124 offset:20224
	v_add_f32_dpp v142, v142, v142 quad_perm:[2,3,0,1] row_mask:0xf bank_mask:0xf bound_ctrl:1
	v_add_f32_dpp v143, v143, v143 quad_perm:[2,3,0,1] row_mask:0xf bank_mask:0xf bound_ctrl:1
	ds_read_b128 v[182:185], v124 offset:20480
	v_add_f32_dpp v142, v142, v142 row_half_mirror row_mask:0xf bank_mask:0xf bound_ctrl:1
	v_add_f32_dpp v143, v143, v143 row_half_mirror row_mask:0xf bank_mask:0xf bound_ctrl:1
	ds_read_b128 v[186:189], v124 offset:20496
	ds_read_b128 v[190:193], v124 offset:20736
	ds_read_b128 v[194:197], v124 offset:20752
	ds_read_b128 v[144:147], v124 offset:19968
	ds_read_b128 v[148:151], v124 offset:19984
	v_pk_mul_f32 v[68:69], v[68:69], v[142:143] op_sel_hi:[1,0]
	v_pk_mul_f32 v[70:71], v[70:71], v[142:143] op_sel_hi:[1,0]
	s_lshl_b64 vcc, vcc, 1
	v_pk_mul_f32 v[56:57], v[56:57], v[142:143] op_sel_hi:[1,0]
	v_pk_mul_f32 v[58:59], v[58:59], v[142:143] op_sel_hi:[1,0]
	v_pk_fma_f32 v[64:65], v[64:65], v[160:161], v[68:69] op_sel_hi:[1,0,1] neg_lo:[0,0,1] neg_hi:[0,0,1]
	v_pk_fma_f32 v[66:67], v[66:67], v[160:161], v[70:71] op_sel_hi:[1,0,1] neg_lo:[0,0,1] neg_hi:[0,0,1]
	v_cndmask_b32_e32 v133, v133, v143, vcc
	v_pk_fma_f32 v[60:61], v[60:61], v[160:161], v[56:57] op_sel_hi:[1,0,1] neg_lo:[0,0,1] neg_hi:[0,0,1]
	v_pk_fma_f32 v[62:63], v[62:63], v[160:161], v[58:59] op_sel_hi:[1,0,1] neg_lo:[0,0,1] neg_hi:[0,0,1]
	ds_read_b128 v[202:205], v124 offset:21008
	ds_read_b128 v[198:201], v124 offset:20992
	v_pk_fma_f32 v[36:37], v[36:37], v[48:49], v[64:65]
	v_pk_fma_f32 v[38:39], v[38:39], v[50:51], v[66:67]
	v_pk_fma_f32 v[32:33], v[32:33], v[40:41], v[60:61]
	v_pk_fma_f32 v[34:35], v[34:35], v[42:43], v[62:63]
	s_waitcnt lgkmcnt(2)
	v_pk_mul_f32 v[156:157], v[32:33], v[156:157]
	v_pk_mul_f32 v[52:53], v[32:33], v[52:53]
	v_pk_mul_f32 v[158:159], v[34:35], v[158:159]
	v_pk_mul_f32 v[54:55], v[34:35], v[54:55]
	v_pk_fma_f32 v[152:153], v[36:37], v[152:153], v[156:157]
	v_pk_fma_f32 v[44:45], v[36:37], v[44:45], v[52:53]
	v_pk_fma_f32 v[154:155], v[38:39], v[154:155], v[158:159]
	v_pk_fma_f32 v[46:47], v[38:39], v[46:47], v[54:55]
	v_pk_add_f32 v[152:153], v[152:153], v[154:155]
	v_pk_add_f32 v[44:45], v[44:45], v[46:47]
	v_add_f32_e32 v142, v152, v153
	v_add_f32_e32 v143, v44, v45
	ds_read_b128 v[76:79], v124 offset:21776
	v_add_f32_dpp v142, v142, v142 quad_perm:[1,0,3,2] row_mask:0xf bank_mask:0xf bound_ctrl:1
	v_add_f32_dpp v143, v143, v143 quad_perm:[1,0,3,2] row_mask:0xf bank_mask:0xf bound_ctrl:1
	ds_read_b128 v[72:75], v124 offset:21760
	v_add_f32_dpp v142, v142, v142 quad_perm:[2,3,0,1] row_mask:0xf bank_mask:0xf bound_ctrl:1
	v_add_f32_dpp v143, v143, v143 quad_perm:[2,3,0,1] row_mask:0xf bank_mask:0xf bound_ctrl:1
	ds_read_b128 v[68:71], v124 offset:22016
	v_add_f32_dpp v142, v142, v142 row_half_mirror row_mask:0xf bank_mask:0xf bound_ctrl:1
	v_add_f32_dpp v143, v143, v143 row_half_mirror row_mask:0xf bank_mask:0xf bound_ctrl:1
	ds_read_b128 v[56:59], v124 offset:22032
	ds_read2st64_b32 v[126:127], v135 offset0:89 offset1:95
	ds_read_b128 v[64:67], v124 offset:22272
	ds_read_b128 v[60:63], v124 offset:22288
	ds_read_b128 v[48:51], v124 offset:21504
	ds_read_b128 v[40:43], v124 offset:21520
	v_pk_mul_f32 v[182:183], v[182:183], v[142:143] op_sel_hi:[1,0]
	v_pk_mul_f32 v[184:185], v[184:185], v[142:143] op_sel_hi:[1,0]
	s_lshl_b64 vcc, vcc, 1
	v_pk_mul_f32 v[186:187], v[186:187], v[142:143] op_sel_hi:[1,0]
	v_pk_mul_f32 v[188:189], v[188:189], v[142:143] op_sel_hi:[1,0]
	v_pk_fma_f32 v[190:191], v[190:191], v[160:161], v[182:183] op_sel:[0,1,0] op_sel_hi:[1,1,1] neg_lo:[0,0,1] neg_hi:[0,0,1]
	v_pk_fma_f32 v[192:193], v[192:193], v[160:161], v[184:185] op_sel:[0,1,0] op_sel_hi:[1,1,1] neg_lo:[0,0,1] neg_hi:[0,0,1]
	v_cndmask_b32_e32 v133, v133, v143, vcc
	v_pk_fma_f32 v[194:195], v[194:195], v[160:161], v[186:187] op_sel:[0,1,0] op_sel_hi:[1,1,1] neg_lo:[0,0,1] neg_hi:[0,0,1]
	v_pk_fma_f32 v[196:197], v[196:197], v[160:161], v[188:189] op_sel:[0,1,0] op_sel_hi:[1,1,1] neg_lo:[0,0,1] neg_hi:[0,0,1]
	ds_read_b128 v[52:55], v124 offset:22544
	ds_read_b128 v[44:47], v124 offset:22528
	v_pk_fma_f32 v[36:37], v[36:37], v[144:145], v[190:191]
	v_pk_fma_f32 v[38:39], v[38:39], v[146:147], v[192:193]
	v_pk_fma_f32 v[32:33], v[32:33], v[148:149], v[194:195]
	v_pk_fma_f32 v[34:35], v[34:35], v[150:151], v[196:197]
	s_waitcnt lgkmcnt(2)
	v_pk_mul_f32 v[76:77], v[32:33], v[76:77]
	v_pk_mul_f32 v[202:203], v[32:33], v[202:203]
	v_pk_mul_f32 v[78:79], v[34:35], v[78:79]
	v_pk_mul_f32 v[204:205], v[34:35], v[204:205]
	v_pk_fma_f32 v[72:73], v[36:37], v[72:73], v[76:77]
	v_pk_fma_f32 v[198:199], v[36:37], v[198:199], v[202:203]
	v_pk_fma_f32 v[74:75], v[38:39], v[74:75], v[78:79]
	v_pk_fma_f32 v[200:201], v[38:39], v[200:201], v[204:205]
	v_pk_add_f32 v[72:73], v[72:73], v[74:75]
	v_pk_add_f32 v[198:199], v[198:199], v[200:201]
	v_add_f32_e32 v142, v72, v73
	v_add_f32_e32 v143, v198, v199
	ds_read_b128 v[156:159], v124 offset:23312
	v_add_f32_dpp v142, v142, v142 quad_perm:[1,0,3,2] row_mask:0xf bank_mask:0xf bound_ctrl:1
	v_add_f32_dpp v143, v143, v143 quad_perm:[1,0,3,2] row_mask:0xf bank_mask:0xf bound_ctrl:1
	ds_read_b128 v[152:155], v124 offset:23296
	v_add_f32_dpp v142, v142, v142 quad_perm:[2,3,0,1] row_mask:0xf bank_mask:0xf bound_ctrl:1
	v_add_f32_dpp v143, v143, v143 quad_perm:[2,3,0,1] row_mask:0xf bank_mask:0xf bound_ctrl:1
	ds_read_b128 v[182:185], v124 offset:23552
	v_add_f32_dpp v142, v142, v142 row_half_mirror row_mask:0xf bank_mask:0xf bound_ctrl:1
	v_add_f32_dpp v143, v143, v143 row_half_mirror row_mask:0xf bank_mask:0xf bound_ctrl:1
	ds_read_b128 v[186:189], v124 offset:23568
	ds_read_b128 v[190:193], v124 offset:23808
	ds_read_b128 v[194:197], v124 offset:23824
	ds_read_b128 v[144:147], v124 offset:23040
	ds_read_b128 v[148:151], v124 offset:23056
	v_pk_mul_f32 v[68:69], v[68:69], v[142:143] op_sel_hi:[1,0]
	v_pk_mul_f32 v[70:71], v[70:71], v[142:143] op_sel_hi:[1,0]
	s_lshl_b64 vcc, vcc, 1
	v_pk_mul_f32 v[56:57], v[56:57], v[142:143] op_sel_hi:[1,0]
	v_pk_mul_f32 v[58:59], v[58:59], v[142:143] op_sel_hi:[1,0]
	v_pk_fma_f32 v[64:65], v[64:65], v[126:127], v[68:69] op_sel_hi:[1,0,1] neg_lo:[0,0,1] neg_hi:[0,0,1]
	v_pk_fma_f32 v[66:67], v[66:67], v[126:127], v[70:71] op_sel_hi:[1,0,1] neg_lo:[0,0,1] neg_hi:[0,0,1]
	v_cndmask_b32_e32 v133, v133, v143, vcc
	v_pk_fma_f32 v[60:61], v[60:61], v[126:127], v[56:57] op_sel_hi:[1,0,1] neg_lo:[0,0,1] neg_hi:[0,0,1]
	v_pk_fma_f32 v[62:63], v[62:63], v[126:127], v[58:59] op_sel_hi:[1,0,1] neg_lo:[0,0,1] neg_hi:[0,0,1]
	ds_read_b128 v[202:205], v124 offset:24080
	ds_read_b128 v[198:201], v124 offset:24064
	v_pk_fma_f32 v[36:37], v[36:37], v[48:49], v[64:65]
	v_pk_fma_f32 v[38:39], v[38:39], v[50:51], v[66:67]
	v_pk_fma_f32 v[32:33], v[32:33], v[40:41], v[60:61]
	v_pk_fma_f32 v[34:35], v[34:35], v[42:43], v[62:63]
	s_waitcnt lgkmcnt(2)
	v_pk_mul_f32 v[156:157], v[32:33], v[156:157]
	v_pk_mul_f32 v[52:53], v[32:33], v[52:53]
	v_pk_mul_f32 v[158:159], v[34:35], v[158:159]
	v_pk_mul_f32 v[54:55], v[34:35], v[54:55]
	v_pk_fma_f32 v[152:153], v[36:37], v[152:153], v[156:157]
	v_pk_fma_f32 v[44:45], v[36:37], v[44:45], v[52:53]
	v_pk_fma_f32 v[154:155], v[38:39], v[154:155], v[158:159]
	v_pk_fma_f32 v[46:47], v[38:39], v[46:47], v[54:55]
	v_pk_add_f32 v[152:153], v[152:153], v[154:155]
	v_pk_add_f32 v[44:45], v[44:45], v[46:47]
	v_add_f32_e32 v142, v152, v153
	v_add_f32_e32 v143, v44, v45
	ds_read_b128 v[76:79], v124 offset:24848
	v_add_f32_dpp v142, v142, v142 quad_perm:[1,0,3,2] row_mask:0xf bank_mask:0xf bound_ctrl:1
	v_add_f32_dpp v143, v143, v143 quad_perm:[1,0,3,2] row_mask:0xf bank_mask:0xf bound_ctrl:1
	ds_read_b128 v[72:75], v124 offset:24832
	v_add_f32_dpp v142, v142, v142 quad_perm:[2,3,0,1] row_mask:0xf bank_mask:0xf bound_ctrl:1
	v_add_f32_dpp v143, v143, v143 quad_perm:[2,3,0,1] row_mask:0xf bank_mask:0xf bound_ctrl:1
	ds_read_b128 v[68:71], v124 offset:25088
	v_add_f32_dpp v142, v142, v142 row_half_mirror row_mask:0xf bank_mask:0xf bound_ctrl:1
	v_add_f32_dpp v143, v143, v143 row_half_mirror row_mask:0xf bank_mask:0xf bound_ctrl:1
	ds_read_b128 v[56:59], v124 offset:25104
	ds_read2st64_b32 v[160:161], v135 offset0:101 offset1:107
	ds_read_b128 v[64:67], v124 offset:25344
	ds_read_b128 v[60:63], v124 offset:25360
	ds_read_b128 v[48:51], v124 offset:24576
	ds_read_b128 v[40:43], v124 offset:24592
	v_pk_mul_f32 v[182:183], v[182:183], v[142:143] op_sel_hi:[1,0]
	v_pk_mul_f32 v[184:185], v[184:185], v[142:143] op_sel_hi:[1,0]
	s_lshl_b64 vcc, vcc, 1
	v_pk_mul_f32 v[186:187], v[186:187], v[142:143] op_sel_hi:[1,0]
	v_pk_mul_f32 v[188:189], v[188:189], v[142:143] op_sel_hi:[1,0]
	v_pk_fma_f32 v[190:191], v[190:191], v[126:127], v[182:183] op_sel:[0,1,0] op_sel_hi:[1,1,1] neg_lo:[0,0,1] neg_hi:[0,0,1]
	v_pk_fma_f32 v[192:193], v[192:193], v[126:127], v[184:185] op_sel:[0,1,0] op_sel_hi:[1,1,1] neg_lo:[0,0,1] neg_hi:[0,0,1]
	v_cndmask_b32_e32 v133, v133, v143, vcc
	v_pk_fma_f32 v[194:195], v[194:195], v[126:127], v[186:187] op_sel:[0,1,0] op_sel_hi:[1,1,1] neg_lo:[0,0,1] neg_hi:[0,0,1]
	v_pk_fma_f32 v[196:197], v[196:197], v[126:127], v[188:189] op_sel:[0,1,0] op_sel_hi:[1,1,1] neg_lo:[0,0,1] neg_hi:[0,0,1]
	ds_read_b128 v[52:55], v124 offset:25616
	ds_read_b128 v[44:47], v124 offset:25600
	v_pk_fma_f32 v[36:37], v[36:37], v[144:145], v[190:191]
	v_pk_fma_f32 v[38:39], v[38:39], v[146:147], v[192:193]
	v_pk_fma_f32 v[32:33], v[32:33], v[148:149], v[194:195]
	v_pk_fma_f32 v[34:35], v[34:35], v[150:151], v[196:197]
	s_waitcnt lgkmcnt(2)
	v_pk_mul_f32 v[76:77], v[32:33], v[76:77]
	v_pk_mul_f32 v[202:203], v[32:33], v[202:203]
	v_pk_mul_f32 v[78:79], v[34:35], v[78:79]
	v_pk_mul_f32 v[204:205], v[34:35], v[204:205]
	v_pk_fma_f32 v[72:73], v[36:37], v[72:73], v[76:77]
	v_pk_fma_f32 v[198:199], v[36:37], v[198:199], v[202:203]
	v_pk_fma_f32 v[74:75], v[38:39], v[74:75], v[78:79]
	v_pk_fma_f32 v[200:201], v[38:39], v[200:201], v[204:205]
	v_pk_add_f32 v[72:73], v[72:73], v[74:75]
	v_pk_add_f32 v[198:199], v[198:199], v[200:201]
	v_add_f32_e32 v142, v72, v73
	v_add_f32_e32 v143, v198, v199
	ds_read_b128 v[156:159], v124 offset:26384
	v_add_f32_dpp v142, v142, v142 quad_perm:[1,0,3,2] row_mask:0xf bank_mask:0xf bound_ctrl:1
	v_add_f32_dpp v143, v143, v143 quad_perm:[1,0,3,2] row_mask:0xf bank_mask:0xf bound_ctrl:1
	ds_read_b128 v[152:155], v124 offset:26368
	v_add_f32_dpp v142, v142, v142 quad_perm:[2,3,0,1] row_mask:0xf bank_mask:0xf bound_ctrl:1
	v_add_f32_dpp v143, v143, v143 quad_perm:[2,3,0,1] row_mask:0xf bank_mask:0xf bound_ctrl:1
	ds_read_b128 v[182:185], v124 offset:26624
	v_add_f32_dpp v142, v142, v142 row_half_mirror row_mask:0xf bank_mask:0xf bound_ctrl:1
	v_add_f32_dpp v143, v143, v143 row_half_mirror row_mask:0xf bank_mask:0xf bound_ctrl:1
	ds_read_b128 v[186:189], v124 offset:26640
	ds_read_b128 v[190:193], v124 offset:26880
	ds_read_b128 v[194:197], v124 offset:26896
	ds_read_b128 v[144:147], v124 offset:26112
	ds_read_b128 v[148:151], v124 offset:26128
	v_pk_mul_f32 v[68:69], v[68:69], v[142:143] op_sel_hi:[1,0]
	v_pk_mul_f32 v[70:71], v[70:71], v[142:143] op_sel_hi:[1,0]
	s_lshl_b64 vcc, vcc, 1
	v_pk_mul_f32 v[56:57], v[56:57], v[142:143] op_sel_hi:[1,0]
	v_pk_mul_f32 v[58:59], v[58:59], v[142:143] op_sel_hi:[1,0]
	v_pk_fma_f32 v[64:65], v[64:65], v[160:161], v[68:69] op_sel_hi:[1,0,1] neg_lo:[0,0,1] neg_hi:[0,0,1]
	v_pk_fma_f32 v[66:67], v[66:67], v[160:161], v[70:71] op_sel_hi:[1,0,1] neg_lo:[0,0,1] neg_hi:[0,0,1]
	v_cndmask_b32_e32 v133, v133, v143, vcc
	v_pk_fma_f32 v[60:61], v[60:61], v[160:161], v[56:57] op_sel_hi:[1,0,1] neg_lo:[0,0,1] neg_hi:[0,0,1]
	v_pk_fma_f32 v[62:63], v[62:63], v[160:161], v[58:59] op_sel_hi:[1,0,1] neg_lo:[0,0,1] neg_hi:[0,0,1]
	ds_read_b128 v[202:205], v124 offset:27152
	ds_read_b128 v[198:201], v124 offset:27136
	v_pk_fma_f32 v[36:37], v[36:37], v[48:49], v[64:65]
	v_pk_fma_f32 v[38:39], v[38:39], v[50:51], v[66:67]
	v_pk_fma_f32 v[32:33], v[32:33], v[40:41], v[60:61]
	v_pk_fma_f32 v[34:35], v[34:35], v[42:43], v[62:63]
	s_waitcnt lgkmcnt(2)
	v_pk_mul_f32 v[156:157], v[32:33], v[156:157]
	v_pk_mul_f32 v[52:53], v[32:33], v[52:53]
	v_pk_mul_f32 v[158:159], v[34:35], v[158:159]
	v_pk_mul_f32 v[54:55], v[34:35], v[54:55]
	v_pk_fma_f32 v[152:153], v[36:37], v[152:153], v[156:157]
	v_pk_fma_f32 v[44:45], v[36:37], v[44:45], v[52:53]
	v_pk_fma_f32 v[154:155], v[38:39], v[154:155], v[158:159]
	v_pk_fma_f32 v[46:47], v[38:39], v[46:47], v[54:55]
	v_pk_add_f32 v[152:153], v[152:153], v[154:155]
	v_pk_add_f32 v[44:45], v[44:45], v[46:47]
	v_add_f32_e32 v142, v152, v153
	v_add_f32_e32 v143, v44, v45
	ds_read_b128 v[76:79], v124 offset:27920
	v_add_f32_dpp v142, v142, v142 quad_perm:[1,0,3,2] row_mask:0xf bank_mask:0xf bound_ctrl:1
	v_add_f32_dpp v143, v143, v143 quad_perm:[1,0,3,2] row_mask:0xf bank_mask:0xf bound_ctrl:1
	ds_read_b128 v[72:75], v124 offset:27904
	v_add_f32_dpp v142, v142, v142 quad_perm:[2,3,0,1] row_mask:0xf bank_mask:0xf bound_ctrl:1
	v_add_f32_dpp v143, v143, v143 quad_perm:[2,3,0,1] row_mask:0xf bank_mask:0xf bound_ctrl:1
	ds_read_b128 v[68:71], v124 offset:28160
	v_add_f32_dpp v142, v142, v142 row_half_mirror row_mask:0xf bank_mask:0xf bound_ctrl:1
	v_add_f32_dpp v143, v143, v143 row_half_mirror row_mask:0xf bank_mask:0xf bound_ctrl:1
	ds_read_b128 v[56:59], v124 offset:28176
	ds_read2st64_b32 v[126:127], v135 offset0:113 offset1:119
	ds_read_b128 v[64:67], v124 offset:28416
	ds_read_b128 v[60:63], v124 offset:28432
	ds_read_b128 v[48:51], v124 offset:27648
	ds_read_b128 v[40:43], v124 offset:27664
	v_pk_mul_f32 v[182:183], v[182:183], v[142:143] op_sel_hi:[1,0]
	v_pk_mul_f32 v[184:185], v[184:185], v[142:143] op_sel_hi:[1,0]
	s_lshr_b64 vcc, vcc, 7
	v_pk_mul_f32 v[186:187], v[186:187], v[142:143] op_sel_hi:[1,0]
	v_pk_mul_f32 v[188:189], v[188:189], v[142:143] op_sel_hi:[1,0]
	v_pk_fma_f32 v[190:191], v[190:191], v[160:161], v[182:183] op_sel:[0,1,0] op_sel_hi:[1,1,1] neg_lo:[0,0,1] neg_hi:[0,0,1]
	v_pk_fma_f32 v[192:193], v[192:193], v[160:161], v[184:185] op_sel:[0,1,0] op_sel_hi:[1,1,1] neg_lo:[0,0,1] neg_hi:[0,0,1]
	v_cndmask_b32_e32 v132, v132, v143, vcc
	v_pk_fma_f32 v[194:195], v[194:195], v[160:161], v[186:187] op_sel:[0,1,0] op_sel_hi:[1,1,1] neg_lo:[0,0,1] neg_hi:[0,0,1]
	v_pk_fma_f32 v[196:197], v[196:197], v[160:161], v[188:189] op_sel:[0,1,0] op_sel_hi:[1,1,1] neg_lo:[0,0,1] neg_hi:[0,0,1]
	ds_read_b128 v[52:55], v124 offset:28688
	ds_read_b128 v[44:47], v124 offset:28672
	v_pk_fma_f32 v[36:37], v[36:37], v[144:145], v[190:191]
	v_pk_fma_f32 v[38:39], v[38:39], v[146:147], v[192:193]
	v_pk_fma_f32 v[32:33], v[32:33], v[148:149], v[194:195]
	v_pk_fma_f32 v[34:35], v[34:35], v[150:151], v[196:197]
	s_waitcnt lgkmcnt(2)
	v_pk_mul_f32 v[76:77], v[32:33], v[76:77]
	v_pk_mul_f32 v[202:203], v[32:33], v[202:203]
	v_pk_mul_f32 v[78:79], v[34:35], v[78:79]
	v_pk_mul_f32 v[204:205], v[34:35], v[204:205]
	v_pk_fma_f32 v[72:73], v[36:37], v[72:73], v[76:77]
	v_pk_fma_f32 v[198:199], v[36:37], v[198:199], v[202:203]
	v_pk_fma_f32 v[74:75], v[38:39], v[74:75], v[78:79]
	v_pk_fma_f32 v[200:201], v[38:39], v[200:201], v[204:205]
	v_pk_add_f32 v[72:73], v[72:73], v[74:75]
	v_pk_add_f32 v[198:199], v[198:199], v[200:201]
	v_add_f32_e32 v142, v72, v73
	v_add_f32_e32 v143, v198, v199
	ds_read_b128 v[156:159], v124 offset:29456
	v_add_f32_dpp v142, v142, v142 quad_perm:[1,0,3,2] row_mask:0xf bank_mask:0xf bound_ctrl:1
	v_add_f32_dpp v143, v143, v143 quad_perm:[1,0,3,2] row_mask:0xf bank_mask:0xf bound_ctrl:1
	ds_read_b128 v[152:155], v124 offset:29440
	v_add_f32_dpp v142, v142, v142 quad_perm:[2,3,0,1] row_mask:0xf bank_mask:0xf bound_ctrl:1
	v_add_f32_dpp v143, v143, v143 quad_perm:[2,3,0,1] row_mask:0xf bank_mask:0xf bound_ctrl:1
	ds_read_b128 v[182:185], v124 offset:29696
	v_add_f32_dpp v142, v142, v142 row_half_mirror row_mask:0xf bank_mask:0xf bound_ctrl:1
	v_add_f32_dpp v143, v143, v143 row_half_mirror row_mask:0xf bank_mask:0xf bound_ctrl:1
	ds_read_b128 v[186:189], v124 offset:29712
	ds_read_b128 v[190:193], v124 offset:29952
	ds_read_b128 v[194:197], v124 offset:29968
	ds_read_b128 v[144:147], v124 offset:29184
	ds_read_b128 v[148:151], v124 offset:29200
	v_pk_mul_f32 v[68:69], v[68:69], v[142:143] op_sel_hi:[1,0]
	v_pk_mul_f32 v[70:71], v[70:71], v[142:143] op_sel_hi:[1,0]
	s_lshl_b64 vcc, vcc, 1
	v_pk_mul_f32 v[56:57], v[56:57], v[142:143] op_sel_hi:[1,0]
	v_pk_mul_f32 v[58:59], v[58:59], v[142:143] op_sel_hi:[1,0]
	v_pk_fma_f32 v[64:65], v[64:65], v[126:127], v[68:69] op_sel_hi:[1,0,1] neg_lo:[0,0,1] neg_hi:[0,0,1]
	v_pk_fma_f32 v[66:67], v[66:67], v[126:127], v[70:71] op_sel_hi:[1,0,1] neg_lo:[0,0,1] neg_hi:[0,0,1]
	v_cndmask_b32_e32 v132, v132, v143, vcc
	v_pk_fma_f32 v[60:61], v[60:61], v[126:127], v[56:57] op_sel_hi:[1,0,1] neg_lo:[0,0,1] neg_hi:[0,0,1]
	v_pk_fma_f32 v[62:63], v[62:63], v[126:127], v[58:59] op_sel_hi:[1,0,1] neg_lo:[0,0,1] neg_hi:[0,0,1]
	ds_read_b128 v[202:205], v124 offset:30224
	ds_read_b128 v[198:201], v124 offset:30208
	v_pk_fma_f32 v[36:37], v[36:37], v[48:49], v[64:65]
	v_pk_fma_f32 v[38:39], v[38:39], v[50:51], v[66:67]
	v_pk_fma_f32 v[32:33], v[32:33], v[40:41], v[60:61]
	v_pk_fma_f32 v[34:35], v[34:35], v[42:43], v[62:63]
	s_waitcnt lgkmcnt(2)
	v_pk_mul_f32 v[156:157], v[32:33], v[156:157]
	v_pk_mul_f32 v[52:53], v[32:33], v[52:53]
	v_pk_mul_f32 v[158:159], v[34:35], v[158:159]
	v_pk_mul_f32 v[54:55], v[34:35], v[54:55]
	v_pk_fma_f32 v[152:153], v[36:37], v[152:153], v[156:157]
	v_pk_fma_f32 v[44:45], v[36:37], v[44:45], v[52:53]
	v_pk_fma_f32 v[154:155], v[38:39], v[154:155], v[158:159]
	v_pk_fma_f32 v[46:47], v[38:39], v[46:47], v[54:55]
	v_pk_add_f32 v[152:153], v[152:153], v[154:155]
	v_pk_add_f32 v[44:45], v[44:45], v[46:47]
	v_add_f32_e32 v142, v152, v153
	v_add_f32_e32 v143, v44, v45
	ds_read_b128 v[76:79], v124 offset:30992
	v_add_f32_dpp v142, v142, v142 quad_perm:[1,0,3,2] row_mask:0xf bank_mask:0xf bound_ctrl:1
	v_add_f32_dpp v143, v143, v143 quad_perm:[1,0,3,2] row_mask:0xf bank_mask:0xf bound_ctrl:1
	ds_read_b128 v[72:75], v124 offset:30976
	v_add_f32_dpp v142, v142, v142 quad_perm:[2,3,0,1] row_mask:0xf bank_mask:0xf bound_ctrl:1
	v_add_f32_dpp v143, v143, v143 quad_perm:[2,3,0,1] row_mask:0xf bank_mask:0xf bound_ctrl:1
	ds_read_b128 v[68:71], v124 offset:31232
	v_add_f32_dpp v142, v142, v142 row_half_mirror row_mask:0xf bank_mask:0xf bound_ctrl:1
	v_add_f32_dpp v143, v143, v143 row_half_mirror row_mask:0xf bank_mask:0xf bound_ctrl:1
	ds_read_b128 v[56:59], v124 offset:31248
	ds_read2st64_b32 v[160:161], v135 offset0:125 offset1:131
	ds_read_b128 v[64:67], v124 offset:31488
	ds_read_b128 v[60:63], v124 offset:31504
	ds_read_b128 v[48:51], v124 offset:30720
	ds_read_b128 v[40:43], v124 offset:30736
	v_pk_mul_f32 v[182:183], v[182:183], v[142:143] op_sel_hi:[1,0]
	v_pk_mul_f32 v[184:185], v[184:185], v[142:143] op_sel_hi:[1,0]
	s_lshl_b64 vcc, vcc, 1
	v_pk_mul_f32 v[186:187], v[186:187], v[142:143] op_sel_hi:[1,0]
	v_pk_mul_f32 v[188:189], v[188:189], v[142:143] op_sel_hi:[1,0]
	v_pk_fma_f32 v[190:191], v[190:191], v[126:127], v[182:183] op_sel:[0,1,0] op_sel_hi:[1,1,1] neg_lo:[0,0,1] neg_hi:[0,0,1]
	v_pk_fma_f32 v[192:193], v[192:193], v[126:127], v[184:185] op_sel:[0,1,0] op_sel_hi:[1,1,1] neg_lo:[0,0,1] neg_hi:[0,0,1]
	v_cndmask_b32_e32 v132, v132, v143, vcc
	v_pk_fma_f32 v[194:195], v[194:195], v[126:127], v[186:187] op_sel:[0,1,0] op_sel_hi:[1,1,1] neg_lo:[0,0,1] neg_hi:[0,0,1]
	v_pk_fma_f32 v[196:197], v[196:197], v[126:127], v[188:189] op_sel:[0,1,0] op_sel_hi:[1,1,1] neg_lo:[0,0,1] neg_hi:[0,0,1]
	ds_read_b128 v[52:55], v124 offset:31760
	ds_read_b128 v[44:47], v124 offset:31744
	v_pk_fma_f32 v[36:37], v[36:37], v[144:145], v[190:191]
	v_pk_fma_f32 v[38:39], v[38:39], v[146:147], v[192:193]
	v_pk_fma_f32 v[32:33], v[32:33], v[148:149], v[194:195]
	v_pk_fma_f32 v[34:35], v[34:35], v[150:151], v[196:197]
	s_waitcnt lgkmcnt(2)
	v_pk_mul_f32 v[76:77], v[32:33], v[76:77]
	v_pk_mul_f32 v[202:203], v[32:33], v[202:203]
	v_pk_mul_f32 v[78:79], v[34:35], v[78:79]
	v_pk_mul_f32 v[204:205], v[34:35], v[204:205]
	v_pk_fma_f32 v[72:73], v[36:37], v[72:73], v[76:77]
	v_pk_fma_f32 v[198:199], v[36:37], v[198:199], v[202:203]
	v_pk_fma_f32 v[74:75], v[38:39], v[74:75], v[78:79]
	v_pk_fma_f32 v[200:201], v[38:39], v[200:201], v[204:205]
	v_pk_add_f32 v[72:73], v[72:73], v[74:75]
	v_pk_add_f32 v[198:199], v[198:199], v[200:201]
	v_add_f32_e32 v142, v72, v73
	v_add_f32_e32 v143, v198, v199
	ds_read_b128 v[156:159], v124 offset:32528
	v_add_f32_dpp v142, v142, v142 quad_perm:[1,0,3,2] row_mask:0xf bank_mask:0xf bound_ctrl:1
	v_add_f32_dpp v143, v143, v143 quad_perm:[1,0,3,2] row_mask:0xf bank_mask:0xf bound_ctrl:1
	ds_read_b128 v[152:155], v124 offset:32512
	v_add_f32_dpp v142, v142, v142 quad_perm:[2,3,0,1] row_mask:0xf bank_mask:0xf bound_ctrl:1
	v_add_f32_dpp v143, v143, v143 quad_perm:[2,3,0,1] row_mask:0xf bank_mask:0xf bound_ctrl:1
	ds_read_b128 v[182:185], v124 offset:32768
	v_add_f32_dpp v142, v142, v142 row_half_mirror row_mask:0xf bank_mask:0xf bound_ctrl:1
	v_add_f32_dpp v143, v143, v143 row_half_mirror row_mask:0xf bank_mask:0xf bound_ctrl:1
	ds_read_b128 v[186:189], v124 offset:32784
	ds_read_b128 v[190:193], v124 offset:33024
	ds_read_b128 v[194:197], v124 offset:33040
	ds_read_b128 v[144:147], v124 offset:32256
	ds_read_b128 v[148:151], v124 offset:32272
	v_pk_mul_f32 v[68:69], v[68:69], v[142:143] op_sel_hi:[1,0]
	v_pk_mul_f32 v[70:71], v[70:71], v[142:143] op_sel_hi:[1,0]
	s_lshl_b64 vcc, vcc, 1
	v_pk_mul_f32 v[56:57], v[56:57], v[142:143] op_sel_hi:[1,0]
	v_pk_mul_f32 v[58:59], v[58:59], v[142:143] op_sel_hi:[1,0]
	v_pk_fma_f32 v[64:65], v[64:65], v[160:161], v[68:69] op_sel_hi:[1,0,1] neg_lo:[0,0,1] neg_hi:[0,0,1]
	v_pk_fma_f32 v[66:67], v[66:67], v[160:161], v[70:71] op_sel_hi:[1,0,1] neg_lo:[0,0,1] neg_hi:[0,0,1]
	v_cndmask_b32_e32 v132, v132, v143, vcc
	v_pk_fma_f32 v[60:61], v[60:61], v[160:161], v[56:57] op_sel_hi:[1,0,1] neg_lo:[0,0,1] neg_hi:[0,0,1]
	v_pk_fma_f32 v[62:63], v[62:63], v[160:161], v[58:59] op_sel_hi:[1,0,1] neg_lo:[0,0,1] neg_hi:[0,0,1]
	ds_read_b128 v[202:205], v124 offset:33296
	ds_read_b128 v[198:201], v124 offset:33280
	v_pk_fma_f32 v[36:37], v[36:37], v[48:49], v[64:65]
	v_pk_fma_f32 v[38:39], v[38:39], v[50:51], v[66:67]
	v_pk_fma_f32 v[32:33], v[32:33], v[40:41], v[60:61]
	v_pk_fma_f32 v[34:35], v[34:35], v[42:43], v[62:63]
	s_waitcnt lgkmcnt(2)
	v_pk_mul_f32 v[156:157], v[32:33], v[156:157]
	v_pk_mul_f32 v[52:53], v[32:33], v[52:53]
	v_pk_mul_f32 v[158:159], v[34:35], v[158:159]
	v_pk_mul_f32 v[54:55], v[34:35], v[54:55]
	v_pk_fma_f32 v[152:153], v[36:37], v[152:153], v[156:157]
	v_pk_fma_f32 v[44:45], v[36:37], v[44:45], v[52:53]
	v_pk_fma_f32 v[154:155], v[38:39], v[154:155], v[158:159]
	v_pk_fma_f32 v[46:47], v[38:39], v[46:47], v[54:55]
	v_pk_add_f32 v[152:153], v[152:153], v[154:155]
	v_pk_add_f32 v[44:45], v[44:45], v[46:47]
	v_add_f32_e32 v142, v152, v153
	v_add_f32_e32 v143, v44, v45
	ds_read_b128 v[76:79], v124 offset:34064
	v_add_f32_dpp v142, v142, v142 quad_perm:[1,0,3,2] row_mask:0xf bank_mask:0xf bound_ctrl:1
	v_add_f32_dpp v143, v143, v143 quad_perm:[1,0,3,2] row_mask:0xf bank_mask:0xf bound_ctrl:1
	ds_read_b128 v[72:75], v124 offset:34048
	v_add_f32_dpp v142, v142, v142 quad_perm:[2,3,0,1] row_mask:0xf bank_mask:0xf bound_ctrl:1
	v_add_f32_dpp v143, v143, v143 quad_perm:[2,3,0,1] row_mask:0xf bank_mask:0xf bound_ctrl:1
	ds_read_b128 v[68:71], v124 offset:34304
	v_add_f32_dpp v142, v142, v142 row_half_mirror row_mask:0xf bank_mask:0xf bound_ctrl:1
	v_add_f32_dpp v143, v143, v143 row_half_mirror row_mask:0xf bank_mask:0xf bound_ctrl:1
	ds_read_b128 v[56:59], v124 offset:34320
	ds_read2st64_b32 v[126:127], v135 offset0:137 offset1:143
	ds_read_b128 v[64:67], v124 offset:34560
	ds_read_b128 v[60:63], v124 offset:34576
	ds_read_b128 v[48:51], v124 offset:33792
	ds_read_b128 v[40:43], v124 offset:33808
	v_pk_mul_f32 v[182:183], v[182:183], v[142:143] op_sel_hi:[1,0]
	v_pk_mul_f32 v[184:185], v[184:185], v[142:143] op_sel_hi:[1,0]
	s_lshl_b64 vcc, vcc, 1
	v_pk_mul_f32 v[186:187], v[186:187], v[142:143] op_sel_hi:[1,0]
	v_pk_mul_f32 v[188:189], v[188:189], v[142:143] op_sel_hi:[1,0]
	v_pk_fma_f32 v[190:191], v[190:191], v[160:161], v[182:183] op_sel:[0,1,0] op_sel_hi:[1,1,1] neg_lo:[0,0,1] neg_hi:[0,0,1]
	v_pk_fma_f32 v[192:193], v[192:193], v[160:161], v[184:185] op_sel:[0,1,0] op_sel_hi:[1,1,1] neg_lo:[0,0,1] neg_hi:[0,0,1]
	v_cndmask_b32_e32 v132, v132, v143, vcc
	v_pk_fma_f32 v[194:195], v[194:195], v[160:161], v[186:187] op_sel:[0,1,0] op_sel_hi:[1,1,1] neg_lo:[0,0,1] neg_hi:[0,0,1]
	v_pk_fma_f32 v[196:197], v[196:197], v[160:161], v[188:189] op_sel:[0,1,0] op_sel_hi:[1,1,1] neg_lo:[0,0,1] neg_hi:[0,0,1]
	ds_read_b128 v[52:55], v124 offset:34832
	ds_read_b128 v[44:47], v124 offset:34816
	v_pk_fma_f32 v[36:37], v[36:37], v[144:145], v[190:191]
	v_pk_fma_f32 v[38:39], v[38:39], v[146:147], v[192:193]
	v_pk_fma_f32 v[32:33], v[32:33], v[148:149], v[194:195]
	v_pk_fma_f32 v[34:35], v[34:35], v[150:151], v[196:197]
	s_waitcnt lgkmcnt(2)
	v_pk_mul_f32 v[76:77], v[32:33], v[76:77]
	v_pk_mul_f32 v[202:203], v[32:33], v[202:203]
	v_pk_mul_f32 v[78:79], v[34:35], v[78:79]
	v_pk_mul_f32 v[204:205], v[34:35], v[204:205]
	v_pk_fma_f32 v[72:73], v[36:37], v[72:73], v[76:77]
	v_pk_fma_f32 v[198:199], v[36:37], v[198:199], v[202:203]
	v_pk_fma_f32 v[74:75], v[38:39], v[74:75], v[78:79]
	v_pk_fma_f32 v[200:201], v[38:39], v[200:201], v[204:205]
	v_pk_add_f32 v[72:73], v[72:73], v[74:75]
	v_pk_add_f32 v[198:199], v[198:199], v[200:201]
	v_add_f32_e32 v142, v72, v73
	v_add_f32_e32 v143, v198, v199
	ds_read_b128 v[156:159], v124 offset:35600
	v_add_f32_dpp v142, v142, v142 quad_perm:[1,0,3,2] row_mask:0xf bank_mask:0xf bound_ctrl:1
	v_add_f32_dpp v143, v143, v143 quad_perm:[1,0,3,2] row_mask:0xf bank_mask:0xf bound_ctrl:1
	ds_read_b128 v[152:155], v124 offset:35584
	v_add_f32_dpp v142, v142, v142 quad_perm:[2,3,0,1] row_mask:0xf bank_mask:0xf bound_ctrl:1
	v_add_f32_dpp v143, v143, v143 quad_perm:[2,3,0,1] row_mask:0xf bank_mask:0xf bound_ctrl:1
	ds_read_b128 v[182:185], v124 offset:35840
	v_add_f32_dpp v142, v142, v142 row_half_mirror row_mask:0xf bank_mask:0xf bound_ctrl:1
	v_add_f32_dpp v143, v143, v143 row_half_mirror row_mask:0xf bank_mask:0xf bound_ctrl:1
	ds_read_b128 v[186:189], v124 offset:35856
	ds_read_b128 v[190:193], v124 offset:36096
	ds_read_b128 v[194:197], v124 offset:36112
	ds_read_b128 v[144:147], v124 offset:35328
	ds_read_b128 v[148:151], v124 offset:35344
	v_pk_mul_f32 v[68:69], v[68:69], v[142:143] op_sel_hi:[1,0]
	v_pk_mul_f32 v[70:71], v[70:71], v[142:143] op_sel_hi:[1,0]
	s_lshl_b64 vcc, vcc, 1
	v_pk_mul_f32 v[56:57], v[56:57], v[142:143] op_sel_hi:[1,0]
	v_pk_mul_f32 v[58:59], v[58:59], v[142:143] op_sel_hi:[1,0]
	v_pk_fma_f32 v[64:65], v[64:65], v[126:127], v[68:69] op_sel_hi:[1,0,1] neg_lo:[0,0,1] neg_hi:[0,0,1]
	v_pk_fma_f32 v[66:67], v[66:67], v[126:127], v[70:71] op_sel_hi:[1,0,1] neg_lo:[0,0,1] neg_hi:[0,0,1]
	v_cndmask_b32_e32 v132, v132, v143, vcc
	v_pk_fma_f32 v[60:61], v[60:61], v[126:127], v[56:57] op_sel_hi:[1,0,1] neg_lo:[0,0,1] neg_hi:[0,0,1]
	v_pk_fma_f32 v[62:63], v[62:63], v[126:127], v[58:59] op_sel_hi:[1,0,1] neg_lo:[0,0,1] neg_hi:[0,0,1]
	ds_read_b128 v[202:205], v124 offset:36368
	ds_read_b128 v[198:201], v124 offset:36352
	v_pk_fma_f32 v[36:37], v[36:37], v[48:49], v[64:65]
	v_pk_fma_f32 v[38:39], v[38:39], v[50:51], v[66:67]
	v_pk_fma_f32 v[32:33], v[32:33], v[40:41], v[60:61]
	v_pk_fma_f32 v[34:35], v[34:35], v[42:43], v[62:63]
	s_waitcnt lgkmcnt(2)
	v_pk_mul_f32 v[156:157], v[32:33], v[156:157]
	v_pk_mul_f32 v[52:53], v[32:33], v[52:53]
	v_pk_mul_f32 v[158:159], v[34:35], v[158:159]
	v_pk_mul_f32 v[54:55], v[34:35], v[54:55]
	v_pk_fma_f32 v[152:153], v[36:37], v[152:153], v[156:157]
	v_pk_fma_f32 v[44:45], v[36:37], v[44:45], v[52:53]
	v_pk_fma_f32 v[154:155], v[38:39], v[154:155], v[158:159]
	v_pk_fma_f32 v[46:47], v[38:39], v[46:47], v[54:55]
	v_pk_add_f32 v[152:153], v[152:153], v[154:155]
	v_pk_add_f32 v[44:45], v[44:45], v[46:47]
	v_add_f32_e32 v142, v152, v153
	v_add_f32_e32 v143, v44, v45
	ds_read_b128 v[76:79], v124 offset:37136
	v_add_f32_dpp v142, v142, v142 quad_perm:[1,0,3,2] row_mask:0xf bank_mask:0xf bound_ctrl:1
	v_add_f32_dpp v143, v143, v143 quad_perm:[1,0,3,2] row_mask:0xf bank_mask:0xf bound_ctrl:1
	ds_read_b128 v[72:75], v124 offset:37120
	v_add_f32_dpp v142, v142, v142 quad_perm:[2,3,0,1] row_mask:0xf bank_mask:0xf bound_ctrl:1
	v_add_f32_dpp v143, v143, v143 quad_perm:[2,3,0,1] row_mask:0xf bank_mask:0xf bound_ctrl:1
	ds_read_b128 v[68:71], v124 offset:37376
	v_add_f32_dpp v142, v142, v142 row_half_mirror row_mask:0xf bank_mask:0xf bound_ctrl:1
	v_add_f32_dpp v143, v143, v143 row_half_mirror row_mask:0xf bank_mask:0xf bound_ctrl:1
	ds_read_b128 v[56:59], v124 offset:37392
	ds_read2st64_b32 v[160:161], v135 offset0:149 offset1:155
	ds_read_b128 v[64:67], v124 offset:37632
	ds_read_b128 v[60:63], v124 offset:37648
	ds_read_b128 v[48:51], v124 offset:36864
	ds_read_b128 v[40:43], v124 offset:36880
	v_pk_mul_f32 v[182:183], v[182:183], v[142:143] op_sel_hi:[1,0]
	v_pk_mul_f32 v[184:185], v[184:185], v[142:143] op_sel_hi:[1,0]
	s_lshl_b64 vcc, vcc, 1
	v_pk_mul_f32 v[186:187], v[186:187], v[142:143] op_sel_hi:[1,0]
	v_pk_mul_f32 v[188:189], v[188:189], v[142:143] op_sel_hi:[1,0]
	v_pk_fma_f32 v[190:191], v[190:191], v[126:127], v[182:183] op_sel:[0,1,0] op_sel_hi:[1,1,1] neg_lo:[0,0,1] neg_hi:[0,0,1]
	v_pk_fma_f32 v[192:193], v[192:193], v[126:127], v[184:185] op_sel:[0,1,0] op_sel_hi:[1,1,1] neg_lo:[0,0,1] neg_hi:[0,0,1]
	v_cndmask_b32_e32 v132, v132, v143, vcc
	v_pk_fma_f32 v[194:195], v[194:195], v[126:127], v[186:187] op_sel:[0,1,0] op_sel_hi:[1,1,1] neg_lo:[0,0,1] neg_hi:[0,0,1]
	v_pk_fma_f32 v[196:197], v[196:197], v[126:127], v[188:189] op_sel:[0,1,0] op_sel_hi:[1,1,1] neg_lo:[0,0,1] neg_hi:[0,0,1]
	ds_read_b128 v[52:55], v124 offset:37904
	ds_read_b128 v[44:47], v124 offset:37888
	v_pk_fma_f32 v[36:37], v[36:37], v[144:145], v[190:191]
	v_pk_fma_f32 v[38:39], v[38:39], v[146:147], v[192:193]
	v_pk_fma_f32 v[32:33], v[32:33], v[148:149], v[194:195]
	v_pk_fma_f32 v[34:35], v[34:35], v[150:151], v[196:197]
	s_waitcnt lgkmcnt(2)
	v_pk_mul_f32 v[76:77], v[32:33], v[76:77]
	v_pk_mul_f32 v[202:203], v[32:33], v[202:203]
	v_pk_mul_f32 v[78:79], v[34:35], v[78:79]
	v_pk_mul_f32 v[204:205], v[34:35], v[204:205]
	v_pk_fma_f32 v[72:73], v[36:37], v[72:73], v[76:77]
	v_pk_fma_f32 v[198:199], v[36:37], v[198:199], v[202:203]
	v_pk_fma_f32 v[74:75], v[38:39], v[74:75], v[78:79]
	v_pk_fma_f32 v[200:201], v[38:39], v[200:201], v[204:205]
	v_pk_add_f32 v[72:73], v[72:73], v[74:75]
	v_pk_add_f32 v[198:199], v[198:199], v[200:201]
	v_add_f32_e32 v142, v72, v73
	v_add_f32_e32 v143, v198, v199
	ds_read_b128 v[156:159], v124 offset:38672
	v_add_f32_dpp v142, v142, v142 quad_perm:[1,0,3,2] row_mask:0xf bank_mask:0xf bound_ctrl:1
	v_add_f32_dpp v143, v143, v143 quad_perm:[1,0,3,2] row_mask:0xf bank_mask:0xf bound_ctrl:1
	ds_read_b128 v[152:155], v124 offset:38656
	v_add_f32_dpp v142, v142, v142 quad_perm:[2,3,0,1] row_mask:0xf bank_mask:0xf bound_ctrl:1
	v_add_f32_dpp v143, v143, v143 quad_perm:[2,3,0,1] row_mask:0xf bank_mask:0xf bound_ctrl:1
	ds_read_b128 v[182:185], v124 offset:38912
	v_add_f32_dpp v142, v142, v142 row_half_mirror row_mask:0xf bank_mask:0xf bound_ctrl:1
	v_add_f32_dpp v143, v143, v143 row_half_mirror row_mask:0xf bank_mask:0xf bound_ctrl:1
	ds_read_b128 v[186:189], v124 offset:38928
	ds_read_b128 v[190:193], v124 offset:39168
	ds_read_b128 v[194:197], v124 offset:39184
	ds_read_b128 v[144:147], v124 offset:38400
	ds_read_b128 v[148:151], v124 offset:38416
	v_pk_mul_f32 v[68:69], v[68:69], v[142:143] op_sel_hi:[1,0]
	v_pk_mul_f32 v[70:71], v[70:71], v[142:143] op_sel_hi:[1,0]
	s_lshl_b64 vcc, vcc, 1
	v_pk_mul_f32 v[56:57], v[56:57], v[142:143] op_sel_hi:[1,0]
	v_pk_mul_f32 v[58:59], v[58:59], v[142:143] op_sel_hi:[1,0]
	v_pk_fma_f32 v[64:65], v[64:65], v[160:161], v[68:69] op_sel_hi:[1,0,1] neg_lo:[0,0,1] neg_hi:[0,0,1]
	v_pk_fma_f32 v[66:67], v[66:67], v[160:161], v[70:71] op_sel_hi:[1,0,1] neg_lo:[0,0,1] neg_hi:[0,0,1]
	v_cndmask_b32_e32 v132, v132, v143, vcc
	v_pk_fma_f32 v[60:61], v[60:61], v[160:161], v[56:57] op_sel_hi:[1,0,1] neg_lo:[0,0,1] neg_hi:[0,0,1]
	v_pk_fma_f32 v[62:63], v[62:63], v[160:161], v[58:59] op_sel_hi:[1,0,1] neg_lo:[0,0,1] neg_hi:[0,0,1]
	ds_read_b128 v[202:205], v124 offset:39440
	ds_read_b128 v[198:201], v124 offset:39424
	v_pk_fma_f32 v[36:37], v[36:37], v[48:49], v[64:65]
	v_pk_fma_f32 v[38:39], v[38:39], v[50:51], v[66:67]
	v_pk_fma_f32 v[32:33], v[32:33], v[40:41], v[60:61]
	v_pk_fma_f32 v[34:35], v[34:35], v[42:43], v[62:63]
	s_waitcnt lgkmcnt(2)
	v_pk_mul_f32 v[156:157], v[32:33], v[156:157]
	v_pk_mul_f32 v[52:53], v[32:33], v[52:53]
	v_pk_mul_f32 v[158:159], v[34:35], v[158:159]
	v_pk_mul_f32 v[54:55], v[34:35], v[54:55]
	v_pk_fma_f32 v[152:153], v[36:37], v[152:153], v[156:157]
	v_pk_fma_f32 v[44:45], v[36:37], v[44:45], v[52:53]
	v_pk_fma_f32 v[154:155], v[38:39], v[154:155], v[158:159]
	v_pk_fma_f32 v[46:47], v[38:39], v[46:47], v[54:55]
	v_pk_add_f32 v[152:153], v[152:153], v[154:155]
	v_pk_add_f32 v[44:45], v[44:45], v[46:47]
	v_add_f32_e32 v142, v152, v153
	v_add_f32_e32 v143, v44, v45
	ds_read_b128 v[76:79], v124 offset:40208
	v_add_f32_dpp v142, v142, v142 quad_perm:[1,0,3,2] row_mask:0xf bank_mask:0xf bound_ctrl:1
	v_add_f32_dpp v143, v143, v143 quad_perm:[1,0,3,2] row_mask:0xf bank_mask:0xf bound_ctrl:1
	ds_read_b128 v[72:75], v124 offset:40192
	v_add_f32_dpp v142, v142, v142 quad_perm:[2,3,0,1] row_mask:0xf bank_mask:0xf bound_ctrl:1
	v_add_f32_dpp v143, v143, v143 quad_perm:[2,3,0,1] row_mask:0xf bank_mask:0xf bound_ctrl:1
	ds_read_b128 v[68:71], v124 offset:40448
	v_add_f32_dpp v142, v142, v142 row_half_mirror row_mask:0xf bank_mask:0xf bound_ctrl:1
	v_add_f32_dpp v143, v143, v143 row_half_mirror row_mask:0xf bank_mask:0xf bound_ctrl:1
	ds_read_b128 v[56:59], v124 offset:40464
	ds_read2st64_b32 v[126:127], v135 offset0:161 offset1:167
	ds_read_b128 v[64:67], v124 offset:40704
	ds_read_b128 v[60:63], v124 offset:40720
	ds_read_b128 v[48:51], v124 offset:39936
	ds_read_b128 v[40:43], v124 offset:39952
	v_pk_mul_f32 v[182:183], v[182:183], v[142:143] op_sel_hi:[1,0]
	v_pk_mul_f32 v[184:185], v[184:185], v[142:143] op_sel_hi:[1,0]
	s_lshr_b64 vcc, vcc, 7
	v_pk_mul_f32 v[186:187], v[186:187], v[142:143] op_sel_hi:[1,0]
	v_pk_mul_f32 v[188:189], v[188:189], v[142:143] op_sel_hi:[1,0]
	v_pk_fma_f32 v[190:191], v[190:191], v[160:161], v[182:183] op_sel:[0,1,0] op_sel_hi:[1,1,1] neg_lo:[0,0,1] neg_hi:[0,0,1]
	v_pk_fma_f32 v[192:193], v[192:193], v[160:161], v[184:185] op_sel:[0,1,0] op_sel_hi:[1,1,1] neg_lo:[0,0,1] neg_hi:[0,0,1]
	v_cndmask_b32_e32 v131, v131, v143, vcc
	v_pk_fma_f32 v[194:195], v[194:195], v[160:161], v[186:187] op_sel:[0,1,0] op_sel_hi:[1,1,1] neg_lo:[0,0,1] neg_hi:[0,0,1]
	v_pk_fma_f32 v[196:197], v[196:197], v[160:161], v[188:189] op_sel:[0,1,0] op_sel_hi:[1,1,1] neg_lo:[0,0,1] neg_hi:[0,0,1]
	ds_read_b128 v[52:55], v124 offset:40976
	ds_read_b128 v[44:47], v124 offset:40960
	v_pk_fma_f32 v[36:37], v[36:37], v[144:145], v[190:191]
	v_pk_fma_f32 v[38:39], v[38:39], v[146:147], v[192:193]
	v_pk_fma_f32 v[32:33], v[32:33], v[148:149], v[194:195]
	v_pk_fma_f32 v[34:35], v[34:35], v[150:151], v[196:197]
	s_waitcnt lgkmcnt(2)
	v_pk_mul_f32 v[76:77], v[32:33], v[76:77]
	v_pk_mul_f32 v[202:203], v[32:33], v[202:203]
	v_pk_mul_f32 v[78:79], v[34:35], v[78:79]
	v_pk_mul_f32 v[204:205], v[34:35], v[204:205]
	v_pk_fma_f32 v[72:73], v[36:37], v[72:73], v[76:77]
	v_pk_fma_f32 v[198:199], v[36:37], v[198:199], v[202:203]
	v_pk_fma_f32 v[74:75], v[38:39], v[74:75], v[78:79]
	v_pk_fma_f32 v[200:201], v[38:39], v[200:201], v[204:205]
	v_pk_add_f32 v[72:73], v[72:73], v[74:75]
	v_pk_add_f32 v[198:199], v[198:199], v[200:201]
	v_add_f32_e32 v142, v72, v73
	v_add_f32_e32 v143, v198, v199
	ds_read_b128 v[156:159], v124 offset:41744
	v_add_f32_dpp v142, v142, v142 quad_perm:[1,0,3,2] row_mask:0xf bank_mask:0xf bound_ctrl:1
	v_add_f32_dpp v143, v143, v143 quad_perm:[1,0,3,2] row_mask:0xf bank_mask:0xf bound_ctrl:1
	ds_read_b128 v[152:155], v124 offset:41728
	v_add_f32_dpp v142, v142, v142 quad_perm:[2,3,0,1] row_mask:0xf bank_mask:0xf bound_ctrl:1
	v_add_f32_dpp v143, v143, v143 quad_perm:[2,3,0,1] row_mask:0xf bank_mask:0xf bound_ctrl:1
	ds_read_b128 v[182:185], v124 offset:41984
	v_add_f32_dpp v142, v142, v142 row_half_mirror row_mask:0xf bank_mask:0xf bound_ctrl:1
	v_add_f32_dpp v143, v143, v143 row_half_mirror row_mask:0xf bank_mask:0xf bound_ctrl:1
	ds_read_b128 v[186:189], v124 offset:42000
	ds_read_b128 v[190:193], v124 offset:42240
	ds_read_b128 v[194:197], v124 offset:42256
	ds_read_b128 v[144:147], v124 offset:41472
	ds_read_b128 v[148:151], v124 offset:41488
	v_pk_mul_f32 v[68:69], v[68:69], v[142:143] op_sel_hi:[1,0]
	v_pk_mul_f32 v[70:71], v[70:71], v[142:143] op_sel_hi:[1,0]
	s_lshl_b64 vcc, vcc, 1
	v_pk_mul_f32 v[56:57], v[56:57], v[142:143] op_sel_hi:[1,0]
	v_pk_mul_f32 v[58:59], v[58:59], v[142:143] op_sel_hi:[1,0]
	v_pk_fma_f32 v[64:65], v[64:65], v[126:127], v[68:69] op_sel_hi:[1,0,1] neg_lo:[0,0,1] neg_hi:[0,0,1]
	v_pk_fma_f32 v[66:67], v[66:67], v[126:127], v[70:71] op_sel_hi:[1,0,1] neg_lo:[0,0,1] neg_hi:[0,0,1]
	v_cndmask_b32_e32 v131, v131, v143, vcc
	v_pk_fma_f32 v[60:61], v[60:61], v[126:127], v[56:57] op_sel_hi:[1,0,1] neg_lo:[0,0,1] neg_hi:[0,0,1]
	v_pk_fma_f32 v[62:63], v[62:63], v[126:127], v[58:59] op_sel_hi:[1,0,1] neg_lo:[0,0,1] neg_hi:[0,0,1]
	ds_read_b128 v[202:205], v124 offset:42512
	ds_read_b128 v[198:201], v124 offset:42496
	v_pk_fma_f32 v[36:37], v[36:37], v[48:49], v[64:65]
	v_pk_fma_f32 v[38:39], v[38:39], v[50:51], v[66:67]
	v_pk_fma_f32 v[32:33], v[32:33], v[40:41], v[60:61]
	v_pk_fma_f32 v[34:35], v[34:35], v[42:43], v[62:63]
	s_waitcnt lgkmcnt(2)
	v_pk_mul_f32 v[156:157], v[32:33], v[156:157]
	v_pk_mul_f32 v[52:53], v[32:33], v[52:53]
	v_pk_mul_f32 v[158:159], v[34:35], v[158:159]
	v_pk_mul_f32 v[54:55], v[34:35], v[54:55]
	v_pk_fma_f32 v[152:153], v[36:37], v[152:153], v[156:157]
	v_pk_fma_f32 v[44:45], v[36:37], v[44:45], v[52:53]
	v_pk_fma_f32 v[154:155], v[38:39], v[154:155], v[158:159]
	v_pk_fma_f32 v[46:47], v[38:39], v[46:47], v[54:55]
	v_pk_add_f32 v[152:153], v[152:153], v[154:155]
	v_pk_add_f32 v[44:45], v[44:45], v[46:47]
	v_add_f32_e32 v142, v152, v153
	v_add_f32_e32 v143, v44, v45
	ds_read_b128 v[76:79], v124 offset:43280
	v_add_f32_dpp v142, v142, v142 quad_perm:[1,0,3,2] row_mask:0xf bank_mask:0xf bound_ctrl:1
	v_add_f32_dpp v143, v143, v143 quad_perm:[1,0,3,2] row_mask:0xf bank_mask:0xf bound_ctrl:1
	ds_read_b128 v[72:75], v124 offset:43264
	v_add_f32_dpp v142, v142, v142 quad_perm:[2,3,0,1] row_mask:0xf bank_mask:0xf bound_ctrl:1
	v_add_f32_dpp v143, v143, v143 quad_perm:[2,3,0,1] row_mask:0xf bank_mask:0xf bound_ctrl:1
	ds_read_b128 v[68:71], v124 offset:43520
	v_add_f32_dpp v142, v142, v142 row_half_mirror row_mask:0xf bank_mask:0xf bound_ctrl:1
	v_add_f32_dpp v143, v143, v143 row_half_mirror row_mask:0xf bank_mask:0xf bound_ctrl:1
	ds_read_b128 v[56:59], v124 offset:43536
	ds_read2st64_b32 v[160:161], v135 offset0:173 offset1:179
	ds_read_b128 v[64:67], v124 offset:43776
	ds_read_b128 v[60:63], v124 offset:43792
	ds_read_b128 v[48:51], v124 offset:43008
	ds_read_b128 v[40:43], v124 offset:43024
	v_pk_mul_f32 v[182:183], v[182:183], v[142:143] op_sel_hi:[1,0]
	v_pk_mul_f32 v[184:185], v[184:185], v[142:143] op_sel_hi:[1,0]
	s_lshl_b64 vcc, vcc, 1
	v_pk_mul_f32 v[186:187], v[186:187], v[142:143] op_sel_hi:[1,0]
	v_pk_mul_f32 v[188:189], v[188:189], v[142:143] op_sel_hi:[1,0]
	v_pk_fma_f32 v[190:191], v[190:191], v[126:127], v[182:183] op_sel:[0,1,0] op_sel_hi:[1,1,1] neg_lo:[0,0,1] neg_hi:[0,0,1]
	v_pk_fma_f32 v[192:193], v[192:193], v[126:127], v[184:185] op_sel:[0,1,0] op_sel_hi:[1,1,1] neg_lo:[0,0,1] neg_hi:[0,0,1]
	v_cndmask_b32_e32 v131, v131, v143, vcc
	v_pk_fma_f32 v[194:195], v[194:195], v[126:127], v[186:187] op_sel:[0,1,0] op_sel_hi:[1,1,1] neg_lo:[0,0,1] neg_hi:[0,0,1]
	v_pk_fma_f32 v[196:197], v[196:197], v[126:127], v[188:189] op_sel:[0,1,0] op_sel_hi:[1,1,1] neg_lo:[0,0,1] neg_hi:[0,0,1]
	ds_read_b128 v[52:55], v124 offset:44048
	ds_read_b128 v[44:47], v124 offset:44032
	v_pk_fma_f32 v[36:37], v[36:37], v[144:145], v[190:191]
	v_pk_fma_f32 v[38:39], v[38:39], v[146:147], v[192:193]
	v_pk_fma_f32 v[32:33], v[32:33], v[148:149], v[194:195]
	v_pk_fma_f32 v[34:35], v[34:35], v[150:151], v[196:197]
	s_waitcnt lgkmcnt(2)
	v_pk_mul_f32 v[76:77], v[32:33], v[76:77]
	v_pk_mul_f32 v[202:203], v[32:33], v[202:203]
	v_pk_mul_f32 v[78:79], v[34:35], v[78:79]
	v_pk_mul_f32 v[204:205], v[34:35], v[204:205]
	v_pk_fma_f32 v[72:73], v[36:37], v[72:73], v[76:77]
	v_pk_fma_f32 v[198:199], v[36:37], v[198:199], v[202:203]
	v_pk_fma_f32 v[74:75], v[38:39], v[74:75], v[78:79]
	v_pk_fma_f32 v[200:201], v[38:39], v[200:201], v[204:205]
	v_pk_add_f32 v[72:73], v[72:73], v[74:75]
	v_pk_add_f32 v[198:199], v[198:199], v[200:201]
	v_add_f32_e32 v142, v72, v73
	v_add_f32_e32 v143, v198, v199
	ds_read_b128 v[156:159], v124 offset:44816
	v_add_f32_dpp v142, v142, v142 quad_perm:[1,0,3,2] row_mask:0xf bank_mask:0xf bound_ctrl:1
	v_add_f32_dpp v143, v143, v143 quad_perm:[1,0,3,2] row_mask:0xf bank_mask:0xf bound_ctrl:1
	ds_read_b128 v[152:155], v124 offset:44800
	v_add_f32_dpp v142, v142, v142 quad_perm:[2,3,0,1] row_mask:0xf bank_mask:0xf bound_ctrl:1
	v_add_f32_dpp v143, v143, v143 quad_perm:[2,3,0,1] row_mask:0xf bank_mask:0xf bound_ctrl:1
	ds_read_b128 v[182:185], v124 offset:45056
	v_add_f32_dpp v142, v142, v142 row_half_mirror row_mask:0xf bank_mask:0xf bound_ctrl:1
	v_add_f32_dpp v143, v143, v143 row_half_mirror row_mask:0xf bank_mask:0xf bound_ctrl:1
	ds_read_b128 v[186:189], v124 offset:45072
	ds_read_b128 v[190:193], v124 offset:45312
	ds_read_b128 v[194:197], v124 offset:45328
	ds_read_b128 v[144:147], v124 offset:44544
	ds_read_b128 v[148:151], v124 offset:44560
	v_pk_mul_f32 v[68:69], v[68:69], v[142:143] op_sel_hi:[1,0]
	v_pk_mul_f32 v[70:71], v[70:71], v[142:143] op_sel_hi:[1,0]
	s_lshl_b64 vcc, vcc, 1
	v_pk_mul_f32 v[56:57], v[56:57], v[142:143] op_sel_hi:[1,0]
	v_pk_mul_f32 v[58:59], v[58:59], v[142:143] op_sel_hi:[1,0]
	v_pk_fma_f32 v[64:65], v[64:65], v[160:161], v[68:69] op_sel_hi:[1,0,1] neg_lo:[0,0,1] neg_hi:[0,0,1]
	v_pk_fma_f32 v[66:67], v[66:67], v[160:161], v[70:71] op_sel_hi:[1,0,1] neg_lo:[0,0,1] neg_hi:[0,0,1]
	v_cndmask_b32_e32 v131, v131, v143, vcc
	v_pk_fma_f32 v[60:61], v[60:61], v[160:161], v[56:57] op_sel_hi:[1,0,1] neg_lo:[0,0,1] neg_hi:[0,0,1]
	v_pk_fma_f32 v[62:63], v[62:63], v[160:161], v[58:59] op_sel_hi:[1,0,1] neg_lo:[0,0,1] neg_hi:[0,0,1]
	ds_read_b128 v[202:205], v124 offset:45584
	ds_read_b128 v[198:201], v124 offset:45568
	v_pk_fma_f32 v[36:37], v[36:37], v[48:49], v[64:65]
	v_pk_fma_f32 v[38:39], v[38:39], v[50:51], v[66:67]
	v_pk_fma_f32 v[32:33], v[32:33], v[40:41], v[60:61]
	v_pk_fma_f32 v[34:35], v[34:35], v[42:43], v[62:63]
	s_waitcnt lgkmcnt(2)
	v_pk_mul_f32 v[156:157], v[32:33], v[156:157]
	v_pk_mul_f32 v[52:53], v[32:33], v[52:53]
	v_pk_mul_f32 v[158:159], v[34:35], v[158:159]
	v_pk_mul_f32 v[54:55], v[34:35], v[54:55]
	v_pk_fma_f32 v[152:153], v[36:37], v[152:153], v[156:157]
	v_pk_fma_f32 v[44:45], v[36:37], v[44:45], v[52:53]
	v_pk_fma_f32 v[154:155], v[38:39], v[154:155], v[158:159]
	v_pk_fma_f32 v[46:47], v[38:39], v[46:47], v[54:55]
	v_pk_add_f32 v[152:153], v[152:153], v[154:155]
	v_pk_add_f32 v[44:45], v[44:45], v[46:47]
	v_add_f32_e32 v142, v152, v153
	v_add_f32_e32 v143, v44, v45
	ds_read_b128 v[76:79], v124 offset:46352
	v_add_f32_dpp v142, v142, v142 quad_perm:[1,0,3,2] row_mask:0xf bank_mask:0xf bound_ctrl:1
	v_add_f32_dpp v143, v143, v143 quad_perm:[1,0,3,2] row_mask:0xf bank_mask:0xf bound_ctrl:1
	ds_read_b128 v[72:75], v124 offset:46336
	v_add_f32_dpp v142, v142, v142 quad_perm:[2,3,0,1] row_mask:0xf bank_mask:0xf bound_ctrl:1
	v_add_f32_dpp v143, v143, v143 quad_perm:[2,3,0,1] row_mask:0xf bank_mask:0xf bound_ctrl:1
	ds_read_b128 v[68:71], v124 offset:46592
	v_add_f32_dpp v142, v142, v142 row_half_mirror row_mask:0xf bank_mask:0xf bound_ctrl:1
	v_add_f32_dpp v143, v143, v143 row_half_mirror row_mask:0xf bank_mask:0xf bound_ctrl:1
	ds_read_b128 v[56:59], v124 offset:46608
	ds_read2st64_b32 v[126:127], v135 offset0:185 offset1:191
	ds_read_b128 v[64:67], v124 offset:46848
	ds_read_b128 v[60:63], v124 offset:46864
	ds_read_b128 v[48:51], v124 offset:46080
	ds_read_b128 v[40:43], v124 offset:46096
	v_pk_mul_f32 v[182:183], v[182:183], v[142:143] op_sel_hi:[1,0]
	v_pk_mul_f32 v[184:185], v[184:185], v[142:143] op_sel_hi:[1,0]
	s_lshl_b64 vcc, vcc, 1
	v_pk_mul_f32 v[186:187], v[186:187], v[142:143] op_sel_hi:[1,0]
	v_pk_mul_f32 v[188:189], v[188:189], v[142:143] op_sel_hi:[1,0]
	v_pk_fma_f32 v[190:191], v[190:191], v[160:161], v[182:183] op_sel:[0,1,0] op_sel_hi:[1,1,1] neg_lo:[0,0,1] neg_hi:[0,0,1]
	v_pk_fma_f32 v[192:193], v[192:193], v[160:161], v[184:185] op_sel:[0,1,0] op_sel_hi:[1,1,1] neg_lo:[0,0,1] neg_hi:[0,0,1]
	v_cndmask_b32_e32 v131, v131, v143, vcc
	v_pk_fma_f32 v[194:195], v[194:195], v[160:161], v[186:187] op_sel:[0,1,0] op_sel_hi:[1,1,1] neg_lo:[0,0,1] neg_hi:[0,0,1]
	v_pk_fma_f32 v[196:197], v[196:197], v[160:161], v[188:189] op_sel:[0,1,0] op_sel_hi:[1,1,1] neg_lo:[0,0,1] neg_hi:[0,0,1]
	ds_read_b128 v[52:55], v124 offset:47120
	ds_read_b128 v[44:47], v124 offset:47104
	v_pk_fma_f32 v[36:37], v[36:37], v[144:145], v[190:191]
	v_pk_fma_f32 v[38:39], v[38:39], v[146:147], v[192:193]
	v_pk_fma_f32 v[32:33], v[32:33], v[148:149], v[194:195]
	v_pk_fma_f32 v[34:35], v[34:35], v[150:151], v[196:197]
	s_waitcnt lgkmcnt(2)
	v_pk_mul_f32 v[76:77], v[32:33], v[76:77]
	v_pk_mul_f32 v[202:203], v[32:33], v[202:203]
	v_pk_mul_f32 v[78:79], v[34:35], v[78:79]
	v_pk_mul_f32 v[204:205], v[34:35], v[204:205]
	v_pk_fma_f32 v[72:73], v[36:37], v[72:73], v[76:77]
	v_pk_fma_f32 v[198:199], v[36:37], v[198:199], v[202:203]
	v_pk_fma_f32 v[74:75], v[38:39], v[74:75], v[78:79]
	v_pk_fma_f32 v[200:201], v[38:39], v[200:201], v[204:205]
	v_pk_add_f32 v[72:73], v[72:73], v[74:75]
	v_pk_add_f32 v[198:199], v[198:199], v[200:201]
	v_add_f32_e32 v142, v72, v73
	v_add_f32_e32 v143, v198, v199
	ds_read_b128 v[156:159], v124 offset:47888
	v_add_f32_dpp v142, v142, v142 quad_perm:[1,0,3,2] row_mask:0xf bank_mask:0xf bound_ctrl:1
	v_add_f32_dpp v143, v143, v143 quad_perm:[1,0,3,2] row_mask:0xf bank_mask:0xf bound_ctrl:1
	ds_read_b128 v[152:155], v124 offset:47872
	v_add_f32_dpp v142, v142, v142 quad_perm:[2,3,0,1] row_mask:0xf bank_mask:0xf bound_ctrl:1
	v_add_f32_dpp v143, v143, v143 quad_perm:[2,3,0,1] row_mask:0xf bank_mask:0xf bound_ctrl:1
	ds_read_b128 v[182:185], v124 offset:48128
	v_add_f32_dpp v142, v142, v142 row_half_mirror row_mask:0xf bank_mask:0xf bound_ctrl:1
	v_add_f32_dpp v143, v143, v143 row_half_mirror row_mask:0xf bank_mask:0xf bound_ctrl:1
	ds_read_b128 v[186:189], v124 offset:48144
	ds_read_b128 v[190:193], v124 offset:48384
	ds_read_b128 v[194:197], v124 offset:48400
	ds_read_b128 v[144:147], v124 offset:47616
	ds_read_b128 v[148:151], v124 offset:47632
	v_pk_mul_f32 v[68:69], v[68:69], v[142:143] op_sel_hi:[1,0]
	v_pk_mul_f32 v[70:71], v[70:71], v[142:143] op_sel_hi:[1,0]
	s_lshl_b64 vcc, vcc, 1
	v_pk_mul_f32 v[56:57], v[56:57], v[142:143] op_sel_hi:[1,0]
	v_pk_mul_f32 v[58:59], v[58:59], v[142:143] op_sel_hi:[1,0]
	v_pk_fma_f32 v[64:65], v[64:65], v[126:127], v[68:69] op_sel_hi:[1,0,1] neg_lo:[0,0,1] neg_hi:[0,0,1]
	v_pk_fma_f32 v[66:67], v[66:67], v[126:127], v[70:71] op_sel_hi:[1,0,1] neg_lo:[0,0,1] neg_hi:[0,0,1]
	v_cndmask_b32_e32 v131, v131, v143, vcc
	v_pk_fma_f32 v[60:61], v[60:61], v[126:127], v[56:57] op_sel_hi:[1,0,1] neg_lo:[0,0,1] neg_hi:[0,0,1]
	v_pk_fma_f32 v[62:63], v[62:63], v[126:127], v[58:59] op_sel_hi:[1,0,1] neg_lo:[0,0,1] neg_hi:[0,0,1]
	ds_read_b128 v[202:205], v124 offset:48656
	ds_read_b128 v[198:201], v124 offset:48640
	v_pk_fma_f32 v[36:37], v[36:37], v[48:49], v[64:65]
	v_pk_fma_f32 v[38:39], v[38:39], v[50:51], v[66:67]
	v_pk_fma_f32 v[32:33], v[32:33], v[40:41], v[60:61]
	v_pk_fma_f32 v[34:35], v[34:35], v[42:43], v[62:63]
	s_waitcnt lgkmcnt(2)
	v_pk_mul_f32 v[156:157], v[32:33], v[156:157]
	v_pk_mul_f32 v[52:53], v[32:33], v[52:53]
	v_pk_mul_f32 v[158:159], v[34:35], v[158:159]
	v_pk_mul_f32 v[54:55], v[34:35], v[54:55]
	v_pk_fma_f32 v[152:153], v[36:37], v[152:153], v[156:157]
	v_pk_fma_f32 v[44:45], v[36:37], v[44:45], v[52:53]
	v_pk_fma_f32 v[154:155], v[38:39], v[154:155], v[158:159]
	v_pk_fma_f32 v[46:47], v[38:39], v[46:47], v[54:55]
	v_pk_add_f32 v[152:153], v[152:153], v[154:155]
	v_pk_add_f32 v[44:45], v[44:45], v[46:47]
	v_add_f32_e32 v142, v152, v153
	v_add_f32_e32 v143, v44, v45
	s_nop 0
	v_add_f32_dpp v142, v142, v142 quad_perm:[1,0,3,2] row_mask:0xf bank_mask:0xf bound_ctrl:1
	v_add_f32_dpp v143, v143, v143 quad_perm:[1,0,3,2] row_mask:0xf bank_mask:0xf bound_ctrl:1
	s_nop 0
	v_add_f32_dpp v142, v142, v142 quad_perm:[2,3,0,1] row_mask:0xf bank_mask:0xf bound_ctrl:1
	v_add_f32_dpp v143, v143, v143 quad_perm:[2,3,0,1] row_mask:0xf bank_mask:0xf bound_ctrl:1
	s_nop 0
	v_add_f32_dpp v142, v142, v142 row_half_mirror row_mask:0xf bank_mask:0xf bound_ctrl:1
	v_add_f32_dpp v143, v143, v143 row_half_mirror row_mask:0xf bank_mask:0xf bound_ctrl:1
	v_pk_mul_f32 v[182:183], v[182:183], v[142:143] op_sel_hi:[1,0]
	v_pk_mul_f32 v[184:185], v[184:185], v[142:143] op_sel_hi:[1,0]
	s_lshl_b64 vcc, vcc, 1
	v_pk_mul_f32 v[186:187], v[186:187], v[142:143] op_sel_hi:[1,0]
	v_pk_mul_f32 v[188:189], v[188:189], v[142:143] op_sel_hi:[1,0]
	v_pk_fma_f32 v[190:191], v[190:191], v[126:127], v[182:183] op_sel:[0,1,0] op_sel_hi:[1,1,1] neg_lo:[0,0,1] neg_hi:[0,0,1]
	v_pk_fma_f32 v[192:193], v[192:193], v[126:127], v[184:185] op_sel:[0,1,0] op_sel_hi:[1,1,1] neg_lo:[0,0,1] neg_hi:[0,0,1]
	v_cndmask_b32_e32 v131, v131, v143, vcc
	v_pk_fma_f32 v[194:195], v[194:195], v[126:127], v[186:187] op_sel:[0,1,0] op_sel_hi:[1,1,1] neg_lo:[0,0,1] neg_hi:[0,0,1]
	v_pk_fma_f32 v[196:197], v[196:197], v[126:127], v[188:189] op_sel:[0,1,0] op_sel_hi:[1,1,1] neg_lo:[0,0,1] neg_hi:[0,0,1]
	v_pk_fma_f32 v[36:37], v[36:37], v[144:145], v[190:191]
	v_pk_fma_f32 v[38:39], v[38:39], v[146:147], v[192:193]
	v_pk_fma_f32 v[32:33], v[32:33], v[148:149], v[194:195]
	v_pk_fma_f32 v[34:35], v[34:35], v[150:151], v[196:197]
	s_waitcnt lgkmcnt(0)
	v_pk_mul_f32 v[202:203], v[32:33], v[202:203]
	v_pk_mul_f32 v[204:205], v[34:35], v[204:205]
	v_pk_fma_f32 v[198:199], v[36:37], v[198:199], v[202:203]
	v_pk_fma_f32 v[200:201], v[38:39], v[200:201], v[204:205]
	v_pk_add_f32 v[198:199], v[198:199], v[200:201]
	v_add_f32_e32 v143, v198, v199
	s_nop 1
	v_add_f32_dpp v143, v143, v143 quad_perm:[1,0,3,2] row_mask:0xf bank_mask:0xf bound_ctrl:1
	s_nop 1
	v_add_f32_dpp v143, v143, v143 quad_perm:[2,3,0,1] row_mask:0xf bank_mask:0xf bound_ctrl:1
	s_nop 1
	v_add_f32_dpp v143, v143, v143 row_half_mirror row_mask:0xf bank_mask:0xf bound_ctrl:1
	s_lshl_b64 vcc, vcc, 1
	v_cndmask_b32_e32 v131, v131, v143, vcc
	s_setprio 0
	s_add_i32 s70, s64, 1
	s_cmp_eq_u32 s70, s84
	s_cbranch_scc1 .Lrw_epi_last
	s_and_b32 s70, s64, 1
	s_mul_i32 s70, s70, 0x1200
	s_add_u32 s70, s70, 0x19000
	v_mad_u32_u24 v40, v86, 36, v81
	v_lshl_add_u32 v40, v40, 2, s70
	ds_write_b32 v40, v134
	ds_write_b32 v40, v133 offset:1152
	ds_write_b32 v40, v132 offset:2304
	ds_write_b32 v40, v131 offset:3456
	s_mov_b64 s[20:21], 0
	s_branch .LBB0_654
